# all six GEMM K-loops: first K-iteration of every unit peeled, first MFMA per accumulator takes C=0, per-unit accumulator clears (127 v_mov each) removed
# speedup vs baseline: 1.2699x; 1.0013x over previous
; #define PG8_STAGE(bufoff, gbase, voff) do { _Pragma("unroll") for (int _i = 0; _i < 2; ++_i) \
;         __builtin_amdgcn_global_load_lds((const unsigned*)((const char*)(gbase) + (voff)[_i]), (PG8_LAS unsigned*)(lds + (bufoff) + ldsw + _i * 8192), 16, 0, 0); } while (0)
; #define PG8_LDA(dst, b, h) do { _Pragma("unroll") for (int m = 0; m < 4; ++m) _Pragma("unroll") for (int k = 0; k < 2; ++k) dst[m][k] = *(const PG8_LAS bf16x8*)(lds + PG8_SA(b, h) + aoff + m * 2048 + k * 1024); } while (0)
; #define PG8_LDB(dst, b, h) do { _Pragma("unroll") for (int n = 0; n < 2; ++n) _Pragma("unroll") for (int k = 0; k < 2; ++k) dst[n][k] = *(const PG8_LAS bf16x8*)(lds + PG8_SB(b, h) + boff + n * 2048 + k * 1024); } while (0)
; #define PG8_MMA(ai, bj, At, Bt) do { __builtin_amdgcn_s_setprio(1); _Pragma("unroll") for (int m = 0; m < 4; ++m) _Pragma("unroll") for (int n = 0; n < 2; ++n) _Pragma("unroll") for (int k = 0; k < 2; ++k) \
;         acc[ai][bj][m][n] = __builtin_amdgcn_mfma_f32_16x16x32_bf16(Bt[n][k], At[m][k], acc[ai][bj][m][n], 0, 0, 0); __builtin_amdgcn_s_setprio(0); } while (0)
; #define PG8_WAIT_V(n) asm volatile("s_waitcnt vmcnt(" #n ")" ::: "memory")
; #define PG8_WAIT_L(n) asm volatile("s_waitcnt lgkmcnt(" #n ")" ::: "memory")
; #define PG8_BAR __builtin_amdgcn_s_barrier()
; #define PG8_SCHED __builtin_amdgcn_sched_barrier(0)
; template <class Epi, class Sched, bool ALIGN_EPI = false, bool SP2 = false>
; __device__ __forceinline__ void gemm_phase(PG8_LAS unsigned char* lds, const Gemm g, const Sched& S, const Epi& E) {
;     ...
;             PG8_LDB(B0, 0, 0); PG8_LDB(B1, 0, 1); PG8_SCHED; PG8_LDA(At, 0, 0); PG8_STAGE(PG8_SA(1, 1), a1 + hstep, voffA);
;             PG8_WAIT_V(8); PG8_WAIT_L(0); PG8_BAR; PG8_MMA(0, 0, At, B0); PG8_MMA(0, 1, At, B1); PG8_BAR; PG8_SCHED;
;             PG8_LDA(At, 0, 1); PG8_STAGE(PG8_SB(0, 0), b2, voffB); PG8_STAGE(PG8_SB(0, 1), b2 + hstep, voffB); PG8_STAGE(PG8_SA(0, 0), a2, voffA);
.Labo_peel:
	v_or_b32_e32 v68, 0x10000, v180
	v_add_u32_e32 v72, 0x10400, v180
	v_add_u32_e32 v76, 0x10800, v180
	v_add_u32_e32 v80, 0x10c00, v180
	v_or_b32_e32 v174, 0x14000, v180
	v_add_u32_e32 v181, 0x14400, v180
	ds_read_b128 v[68:71], v68
	ds_read_b128 v[72:75], v72
	ds_read_b128 v[76:79], v76
	ds_read_b128 v[80:83], v80
	ds_read_b128 v[174:177], v174
	ds_read_b128 v[182:185], v181
	v_add_u32_e32 v181, 0x14800, v180
	v_add_u32_e32 v190, 0x14c00, v180
	ds_read_b128 v[186:189], v181
	ds_read_b128 v[210:213], v190
	s_add_u32 s2, s0, 0xfffc0080
	s_addc_u32 s3, s1, -1
	s_cmp_eq_u32 s56, 12
	s_cselect_b32 s5, s27, s3
	s_cselect_b32 s4, s52, s2
	s_cselect_b32 s3, s25, s55
	s_cselect_b32 s2, s53, s54
	v_lshl_add_u64 v[190:191], s[0:1], 0, v[170:171]
	s_add_i32 m0, s29, 0xc000
	ds_read_b128 v[214:217], v179
	ds_read_b128 v[218:221], v179 offset:1024
	ds_read_b128 v[222:225], v179 offset:2048
	ds_read_b128 v[226:229], v179 offset:3072
	ds_read_b128 v[230:233], v179 offset:4096
	ds_read_b128 v[234:237], v179 offset:5120
	ds_read_b128 v[238:241], v179 offset:6144
	ds_read_b128 v[242:245], v179 offset:7168
	global_load_lds_dwordx4 v[190:191], off
	v_lshl_add_u64 v[190:191], s[0:1], 0, v[172:173]
	s_add_i32 m0, s29, 0xe000
	s_nop 0
	global_load_lds_dwordx4 v[190:191], off
	s_waitcnt vmcnt(8)
	s_waitcnt lgkmcnt(0)
	s_barrier
	s_setprio 1
	s_waitcnt lgkmcnt(0)
	v_mfma_f32_16x16x32_bf16 v[140:143], v[68:71], v[214:217], 0
	v_mfma_f32_16x16x32_bf16 v[136:139], v[76:79], v[214:217], 0
	v_mfma_f32_16x16x32_bf16 v[124:127], v[68:71], v[222:225], 0
	v_mfma_f32_16x16x32_bf16 v[120:123], v[76:79], v[222:225], 0
	v_mfma_f32_16x16x32_bf16 v[108:111], v[68:71], v[230:233], 0
	v_mfma_f32_16x16x32_bf16 v[104:107], v[76:79], v[230:233], 0
	v_mfma_f32_16x16x32_bf16 v[92:95], v[68:71], v[238:241], 0
	v_mfma_f32_16x16x32_bf16 v[88:91], v[76:79], v[238:241], 0
	v_mfma_f32_16x16x32_bf16 v[140:143], v[72:75], v[218:221], v[140:143]
	v_mfma_f32_16x16x32_bf16 v[136:139], v[80:83], v[218:221], v[136:139]
	v_mfma_f32_16x16x32_bf16 v[124:127], v[72:75], v[226:229], v[124:127]
	v_mfma_f32_16x16x32_bf16 v[120:123], v[80:83], v[226:229], v[120:123]
	v_mfma_f32_16x16x32_bf16 v[108:111], v[72:75], v[234:237], v[108:111]
	v_mfma_f32_16x16x32_bf16 v[104:107], v[80:83], v[234:237], v[104:107]
	v_mfma_f32_16x16x32_bf16 v[92:95], v[72:75], v[242:245], v[92:95]
	v_mfma_f32_16x16x32_bf16 v[88:91], v[80:83], v[242:245], v[88:91]
	s_setprio 0
	s_setprio 1
	v_mfma_f32_16x16x32_bf16 v[132:135], v[174:177], v[214:217], 0
	v_mfma_f32_16x16x32_bf16 v[128:131], v[186:189], v[214:217], 0
	v_mfma_f32_16x16x32_bf16 v[116:119], v[174:177], v[222:225], 0
	v_mfma_f32_16x16x32_bf16 v[112:115], v[186:189], v[222:225], 0
	v_mfma_f32_16x16x32_bf16 v[100:103], v[174:177], v[230:233], 0
	v_mfma_f32_16x16x32_bf16 v[96:99], v[186:189], v[230:233], 0
	v_mfma_f32_16x16x32_bf16 v[84:87], v[174:177], v[238:241], 0
	v_mfma_f32_16x16x32_bf16 v[64:67], v[186:189], v[238:241], 0
	v_mfma_f32_16x16x32_bf16 v[132:135], v[182:185], v[218:221], v[132:135]
	v_mfma_f32_16x16x32_bf16 v[128:131], v[210:213], v[218:221], v[128:131]
	v_mfma_f32_16x16x32_bf16 v[116:119], v[182:185], v[226:229], v[116:119]
	v_mfma_f32_16x16x32_bf16 v[112:115], v[210:213], v[226:229], v[112:115]
	v_mfma_f32_16x16x32_bf16 v[100:103], v[182:185], v[234:237], v[100:103]
	v_mfma_f32_16x16x32_bf16 v[96:99], v[210:213], v[234:237], v[96:99]
	v_mfma_f32_16x16x32_bf16 v[84:87], v[182:185], v[242:245], v[84:87]
	v_mfma_f32_16x16x32_bf16 v[64:67], v[210:213], v[242:245], v[64:67]
	s_setprio 0
	s_barrier
	s_mov_b32 m0, s30
	v_lshl_add_u64 v[190:191], s[2:3], 0, v[166:167]
	s_add_u32 s58, s2, 0x40000
	ds_read_b128 v[214:217], v179 offset:16384
	ds_read_b128 v[218:221], v179 offset:17408
	ds_read_b128 v[222:225], v179 offset:18432
	ds_read_b128 v[226:229], v179 offset:19456
	ds_read_b128 v[230:233], v179 offset:20480
	ds_read_b128 v[234:237], v179 offset:21504
	ds_read_b128 v[238:241], v179 offset:22528
	ds_read_b128 v[242:245], v179 offset:23552
	global_load_lds_dwordx4 v[190:191], off
	v_lshl_add_u64 v[208:209], s[2:3], 0, v[162:163]
	s_mov_b32 m0, s31
	s_addc_u32 s59, s3, 0
	global_load_lds_dwordx4 v[208:209], off
	v_lshl_add_u64 v[246:247], s[58:59], 0, v[166:167]
	s_mov_b32 m0, s33
	v_lshl_add_u64 v[248:249], s[4:5], 0, v[164:165]
	global_load_lds_dwordx4 v[246:247], off
	v_lshl_add_u64 v[246:247], s[58:59], 0, v[162:163]
	s_mov_b32 m0, s34
	s_nop 0
	global_load_lds_dwordx4 v[246:247], off
	v_lshl_add_u64 v[246:247], s[4:5], 0, v[168:169]
	s_mov_b32 m0, s29
	s_nop 0
	global_load_lds_dwordx4 v[246:247], off
	s_mov_b32 m0, s35
	s_nop 0
	global_load_lds_dwordx4 v[248:249], off
	s_waitcnt vmcnt(8)
	s_waitcnt lgkmcnt(0)
	s_barrier
; #define PG8_STAGE(bufoff, gbase, voff) do { _Pragma("unroll") for (int _i = 0; _i < 2; ++_i) \
;         __builtin_amdgcn_global_load_lds((const unsigned*)((const char*)(gbase) + (voff)[_i]), (PG8_LAS unsigned*)(lds + (bufoff) + ldsw + _i * 8192), 16, 0, 0); } while (0)
; #define PG8_LDA(dst, b, h) do { _Pragma("unroll") for (int m = 0; m < 4; ++m) _Pragma("unroll") for (int k = 0; k < 2; ++k) dst[m][k] = *(const PG8_LAS bf16x8*)(lds + PG8_SA(b, h) + aoff + m * 2048 + k * 1024); } while (0)
; #define PG8_LDB(dst, b, h) do { _Pragma("unroll") for (int n = 0; n < 2; ++n) _Pragma("unroll") for (int k = 0; k < 2; ++k) dst[n][k] = *(const PG8_LAS bf16x8*)(lds + PG8_SB(b, h) + boff + n * 2048 + k * 1024); } while (0)
; #define PG8_MMA(ai, bj, At, Bt) do { __builtin_amdgcn_s_setprio(1); _Pragma("unroll") for (int m = 0; m < 4; ++m) _Pragma("unroll") for (int n = 0; n < 2; ++n) _Pragma("unroll") for (int k = 0; k < 2; ++k) \
;         acc[ai][bj][m][n] = __builtin_amdgcn_mfma_f32_16x16x32_bf16(Bt[n][k], At[m][k], acc[ai][bj][m][n], 0, 0, 0); __builtin_amdgcn_s_setprio(0); } while (0)
; #define PG8_WAIT_V(n) asm volatile("s_waitcnt vmcnt(" #n ")" ::: "memory")
; #define PG8_WAIT_L(n) asm volatile("s_waitcnt lgkmcnt(" #n ")" ::: "memory")
; #define PG8_BAR __builtin_amdgcn_s_barrier()
; #define PG8_SCHED __builtin_amdgcn_sched_barrier(0)
; template <class Epi, class Sched, bool ALIGN_EPI = false, bool SP2 = false>
; __device__ __forceinline__ void gemm_phase(PG8_LAS unsigned char* lds, const Gemm g, const Sched& S, const Epi& E) {
;     ...
;             PG8_WAIT_V(8); PG8_WAIT_L(0); PG8_BAR; PG8_MMA(1, 0, At, B0); PG8_MMA(1, 1, At, B1); PG8_BAR; PG8_SCHED;
;             PG8_LDB(B0, 1, 0); PG8_LDB(B1, 1, 1); PG8_SCHED; PG8_LDA(At, 1, 0); PG8_STAGE(PG8_SA(0, 1), a2 + hstep, voffA);
;             PG8_WAIT_V(8); PG8_WAIT_L(0); PG8_BAR; PG8_MMA(0, 0, At, B0); PG8_MMA(0, 1, At, B1); PG8_BAR; PG8_SCHED;
	s_setprio 1
	s_waitcnt lgkmcnt(0)
	v_mfma_f32_16x16x32_bf16 v[60:63], v[68:71], v[214:217], 0
	v_mfma_f32_16x16x32_bf16 v[56:59], v[76:79], v[214:217], 0
	v_mfma_f32_16x16x32_bf16 v[44:47], v[68:71], v[222:225], 0
	v_mfma_f32_16x16x32_bf16 v[40:43], v[76:79], v[222:225], 0
	v_mfma_f32_16x16x32_bf16 v[28:31], v[68:71], v[230:233], 0
	v_mfma_f32_16x16x32_bf16 v[24:27], v[76:79], v[230:233], 0
	v_mfma_f32_16x16x32_bf16 v[12:15], v[68:71], v[238:241], 0
	v_mfma_f32_16x16x32_bf16 v[8:11], v[76:79], v[238:241], 0
	v_mfma_f32_16x16x32_bf16 v[60:63], v[72:75], v[218:221], v[60:63]
	v_mfma_f32_16x16x32_bf16 v[56:59], v[80:83], v[218:221], v[56:59]
	v_mfma_f32_16x16x32_bf16 v[44:47], v[72:75], v[226:229], v[44:47]
	v_mfma_f32_16x16x32_bf16 v[40:43], v[80:83], v[226:229], v[40:43]
	v_mfma_f32_16x16x32_bf16 v[28:31], v[72:75], v[234:237], v[28:31]
	v_mfma_f32_16x16x32_bf16 v[24:27], v[80:83], v[234:237], v[24:27]
	v_mfma_f32_16x16x32_bf16 v[12:15], v[72:75], v[242:245], v[12:15]
	v_mfma_f32_16x16x32_bf16 v[8:11], v[80:83], v[242:245], v[8:11]
	s_setprio 0
	s_setprio 1
	v_mfma_f32_16x16x32_bf16 v[52:55], v[174:177], v[214:217], 0
	v_mfma_f32_16x16x32_bf16 v[48:51], v[186:189], v[214:217], 0
	v_mfma_f32_16x16x32_bf16 v[36:39], v[174:177], v[222:225], 0
	v_mfma_f32_16x16x32_bf16 v[32:35], v[186:189], v[222:225], 0
	v_mfma_f32_16x16x32_bf16 v[20:23], v[174:177], v[230:233], 0
	v_mfma_f32_16x16x32_bf16 v[16:19], v[186:189], v[230:233], 0
	v_mfma_f32_16x16x32_bf16 v[4:7], v[174:177], v[238:241], 0
	v_mfma_f32_16x16x32_bf16 v[0:3], v[186:189], v[238:241], 0
	v_mfma_f32_16x16x32_bf16 v[52:55], v[182:185], v[218:221], v[52:55]
	v_mfma_f32_16x16x32_bf16 v[48:51], v[210:213], v[218:221], v[48:51]
	v_mfma_f32_16x16x32_bf16 v[36:39], v[182:185], v[226:229], v[36:39]
	v_mfma_f32_16x16x32_bf16 v[32:35], v[210:213], v[226:229], v[32:35]
	v_mfma_f32_16x16x32_bf16 v[20:23], v[182:185], v[234:237], v[20:23]
	v_mfma_f32_16x16x32_bf16 v[16:19], v[210:213], v[234:237], v[16:19]
	v_mfma_f32_16x16x32_bf16 v[4:7], v[182:185], v[242:245], v[4:7]
	v_mfma_f32_16x16x32_bf16 v[0:3], v[210:213], v[242:245], v[0:3]
	s_setprio 0
	s_barrier
	v_or_b32_e32 v68, 0x18000, v180
	v_add_u32_e32 v72, 0x18400, v180
	v_add_u32_e32 v76, 0x18800, v180
	v_add_u32_e32 v80, 0x18c00, v180
	v_or_b32_e32 v174, 0x1c000, v180
	v_add_u32_e32 v181, 0x1c400, v180
	ds_read_b128 v[68:71], v68
	ds_read_b128 v[72:75], v72
	ds_read_b128 v[76:79], v76
	ds_read_b128 v[80:83], v80
	ds_read_b128 v[174:177], v174
	ds_read_b128 v[182:185], v181
	v_add_u32_e32 v181, 0x1c800, v180
	v_add_u32_e32 v210, 0x1cc00, v180
	ds_read_b128 v[186:189], v181
	ds_read_b128 v[210:213], v210
	s_add_u32 s4, s4, 0x40000
	s_addc_u32 s5, s5, 0
	s_mov_b32 m0, s40
	v_lshl_add_u64 v[250:251], s[4:5], 0, v[168:169]
	ds_read_b128 v[214:217], v179 offset:32768
	ds_read_b128 v[218:221], v179 offset:33792
	ds_read_b128 v[222:225], v179 offset:34816
	ds_read_b128 v[226:229], v179 offset:35840
	ds_read_b128 v[230:233], v179 offset:36864
	ds_read_b128 v[234:237], v179 offset:37888
	ds_read_b128 v[238:241], v179 offset:38912
	ds_read_b128 v[242:245], v179 offset:39936
	global_load_lds_dwordx4 v[250:251], off
	v_lshl_add_u64 v[250:251], s[4:5], 0, v[164:165]
	s_mov_b32 m0, s41
	s_nop 0
	global_load_lds_dwordx4 v[250:251], off
	s_waitcnt vmcnt(8)
	s_waitcnt lgkmcnt(0)
	s_barrier
	s_setprio 1
	s_waitcnt lgkmcnt(0)
	v_mfma_f32_16x16x32_bf16 v[140:143], v[68:71], v[214:217], v[140:143]
	v_mfma_f32_16x16x32_bf16 v[136:139], v[76:79], v[214:217], v[136:139]
	v_mfma_f32_16x16x32_bf16 v[124:127], v[68:71], v[222:225], v[124:127]
	v_mfma_f32_16x16x32_bf16 v[120:123], v[76:79], v[222:225], v[120:123]
	v_mfma_f32_16x16x32_bf16 v[108:111], v[68:71], v[230:233], v[108:111]
	v_mfma_f32_16x16x32_bf16 v[104:107], v[76:79], v[230:233], v[104:107]
	v_mfma_f32_16x16x32_bf16 v[92:95], v[68:71], v[238:241], v[92:95]
	v_mfma_f32_16x16x32_bf16 v[88:91], v[76:79], v[238:241], v[88:91]
	v_mfma_f32_16x16x32_bf16 v[140:143], v[72:75], v[218:221], v[140:143]
	v_mfma_f32_16x16x32_bf16 v[136:139], v[80:83], v[218:221], v[136:139]
	v_mfma_f32_16x16x32_bf16 v[124:127], v[72:75], v[226:229], v[124:127]
	v_mfma_f32_16x16x32_bf16 v[120:123], v[80:83], v[226:229], v[120:123]
	v_mfma_f32_16x16x32_bf16 v[108:111], v[72:75], v[234:237], v[108:111]
	v_mfma_f32_16x16x32_bf16 v[104:107], v[80:83], v[234:237], v[104:107]
	v_mfma_f32_16x16x32_bf16 v[92:95], v[72:75], v[242:245], v[92:95]
	v_mfma_f32_16x16x32_bf16 v[88:91], v[80:83], v[242:245], v[88:91]
	s_setprio 0
	s_setprio 1
	v_mfma_f32_16x16x32_bf16 v[132:135], v[174:177], v[214:217], v[132:135]
	v_mfma_f32_16x16x32_bf16 v[128:131], v[186:189], v[214:217], v[128:131]
	v_mfma_f32_16x16x32_bf16 v[116:119], v[174:177], v[222:225], v[116:119]
	v_mfma_f32_16x16x32_bf16 v[112:115], v[186:189], v[222:225], v[112:115]
	v_mfma_f32_16x16x32_bf16 v[100:103], v[174:177], v[230:233], v[100:103]
	v_mfma_f32_16x16x32_bf16 v[96:99], v[186:189], v[230:233], v[96:99]
	v_mfma_f32_16x16x32_bf16 v[84:87], v[174:177], v[238:241], v[84:87]
	v_mfma_f32_16x16x32_bf16 v[64:67], v[186:189], v[238:241], v[64:67]
	v_mfma_f32_16x16x32_bf16 v[132:135], v[182:185], v[218:221], v[132:135]
	v_mfma_f32_16x16x32_bf16 v[128:131], v[210:213], v[218:221], v[128:131]
	v_mfma_f32_16x16x32_bf16 v[116:119], v[182:185], v[226:229], v[116:119]
	v_mfma_f32_16x16x32_bf16 v[112:115], v[210:213], v[226:229], v[112:115]
	v_mfma_f32_16x16x32_bf16 v[100:103], v[182:185], v[234:237], v[100:103]
	v_mfma_f32_16x16x32_bf16 v[96:99], v[210:213], v[234:237], v[96:99]
	v_mfma_f32_16x16x32_bf16 v[84:87], v[182:185], v[242:245], v[84:87]
	v_mfma_f32_16x16x32_bf16 v[64:67], v[210:213], v[242:245], v[64:67]
	s_setprio 0
	s_barrier
; #define PG8_STAGE(bufoff, gbase, voff) do { _Pragma("unroll") for (int _i = 0; _i < 2; ++_i) \
;         __builtin_amdgcn_global_load_lds((const unsigned*)((const char*)(gbase) + (voff)[_i]), (PG8_LAS unsigned*)(lds + (bufoff) + ldsw + _i * 8192), 16, 0, 0); } while (0)
; #define PG8_LDA(dst, b, h) do { _Pragma("unroll") for (int m = 0; m < 4; ++m) _Pragma("unroll") for (int k = 0; k < 2; ++k) dst[m][k] = *(const PG8_LAS bf16x8*)(lds + PG8_SA(b, h) + aoff + m * 2048 + k * 1024); } while (0)
; #define PG8_MMA(ai, bj, At, Bt) do { __builtin_amdgcn_s_setprio(1); _Pragma("unroll") for (int m = 0; m < 4; ++m) _Pragma("unroll") for (int n = 0; n < 2; ++n) _Pragma("unroll") for (int k = 0; k < 2; ++k) \
;         acc[ai][bj][m][n] = __builtin_amdgcn_mfma_f32_16x16x32_bf16(Bt[n][k], At[m][k], acc[ai][bj][m][n], 0, 0, 0); __builtin_amdgcn_s_setprio(0); } while (0)
; #define PG8_WAIT_V(n) asm volatile("s_waitcnt vmcnt(" #n ")" ::: "memory")
; #define PG8_WAIT_L(n) asm volatile("s_waitcnt lgkmcnt(" #n ")" ::: "memory")
; #define PG8_BAR __builtin_amdgcn_s_barrier()
; #define PG8_SCHED __builtin_amdgcn_sched_barrier(0)
; template <class Epi, class Sched, bool ALIGN_EPI = false, bool SP2 = false>
; __device__ __forceinline__ void gemm_phase(PG8_LAS unsigned char* lds, const Gemm g, const Sched& S, const Epi& E) {
;     ...
;             PG8_WAIT_V(8); PG8_WAIT_L(0); PG8_BAR; PG8_MMA(0, 0, At, B0); PG8_MMA(0, 1, At, B1); PG8_BAR; PG8_SCHED;
;             PG8_LDA(At, 1, 1); PG8_STAGE(PG8_SB(1, 0), b3, voffB); PG8_STAGE(PG8_SB(1, 1), b3 + hstep, voffB); PG8_STAGE(PG8_SA(1, 0), a3, voffA);
;             PG8_WAIT_V(8); PG8_WAIT_L(0); PG8_BAR; PG8_MMA(1, 0, At, B0); PG8_MMA(1, 1, At, B1); PG8_BAR; PG8_SCHED;
	s_mov_b32 m0, s45
	v_lshl_add_u64 v[190:191], v[190:191], 0, s[94:95]
	s_add_u32 s2, s2, 0x40080
	ds_read_b128 v[214:217], v179 offset:49152
	ds_read_b128 v[218:221], v179 offset:50176
	ds_read_b128 v[222:225], v179 offset:51200
	ds_read_b128 v[226:229], v179 offset:52224
	ds_read_b128 v[230:233], v179 offset:53248
	ds_read_b128 v[234:237], v179 offset:54272
	ds_read_b128 v[238:241], v179 offset:55296
	ds_read_b128 v[242:245], v179 offset:56320
	global_load_lds_dwordx4 v[190:191], off
	v_lshl_add_u64 v[190:191], v[208:209], 0, s[94:95]
	s_mov_b32 m0, s46
	s_addc_u32 s3, s3, 0
	global_load_lds_dwordx4 v[190:191], off
	v_lshl_add_u64 v[190:191], s[2:3], 0, v[166:167]
	s_mov_b32 m0, s49
	s_nop 0
	global_load_lds_dwordx4 v[190:191], off
	v_lshl_add_u64 v[190:191], s[2:3], 0, v[162:163]
	s_mov_b32 m0, s50
	s_nop 0
	global_load_lds_dwordx4 v[190:191], off
	v_lshl_add_u64 v[190:191], v[246:247], 0, s[94:95]
	s_mov_b32 m0, s47
	s_nop 0
	global_load_lds_dwordx4 v[190:191], off
	v_lshl_add_u64 v[190:191], v[248:249], 0, s[94:95]
	s_mov_b32 m0, s48
	s_nop 0
	global_load_lds_dwordx4 v[190:191], off
	s_waitcnt vmcnt(8)
	s_waitcnt lgkmcnt(0)
	s_barrier
	s_setprio 1
	s_waitcnt lgkmcnt(0)
	v_mfma_f32_16x16x32_bf16 v[60:63], v[68:71], v[214:217], v[60:63]
	v_mfma_f32_16x16x32_bf16 v[56:59], v[76:79], v[214:217], v[56:59]
	v_mfma_f32_16x16x32_bf16 v[44:47], v[68:71], v[222:225], v[44:47]
	v_mfma_f32_16x16x32_bf16 v[40:43], v[76:79], v[222:225], v[40:43]
	v_mfma_f32_16x16x32_bf16 v[28:31], v[68:71], v[230:233], v[28:31]
	v_mfma_f32_16x16x32_bf16 v[24:27], v[76:79], v[230:233], v[24:27]
	v_mfma_f32_16x16x32_bf16 v[12:15], v[68:71], v[238:241], v[12:15]
	v_mfma_f32_16x16x32_bf16 v[8:11], v[76:79], v[238:241], v[8:11]
	v_mfma_f32_16x16x32_bf16 v[60:63], v[72:75], v[218:221], v[60:63]
	v_mfma_f32_16x16x32_bf16 v[56:59], v[80:83], v[218:221], v[56:59]
	v_mfma_f32_16x16x32_bf16 v[44:47], v[72:75], v[226:229], v[44:47]
	v_mfma_f32_16x16x32_bf16 v[40:43], v[80:83], v[226:229], v[40:43]
	v_mfma_f32_16x16x32_bf16 v[28:31], v[72:75], v[234:237], v[28:31]
	v_mfma_f32_16x16x32_bf16 v[24:27], v[80:83], v[234:237], v[24:27]
	v_mfma_f32_16x16x32_bf16 v[12:15], v[72:75], v[242:245], v[12:15]
	v_mfma_f32_16x16x32_bf16 v[8:11], v[80:83], v[242:245], v[8:11]
	s_setprio 0
	s_setprio 1
	v_mfma_f32_16x16x32_bf16 v[52:55], v[174:177], v[214:217], v[52:55]
	v_mfma_f32_16x16x32_bf16 v[48:51], v[186:189], v[214:217], v[48:51]
	v_mfma_f32_16x16x32_bf16 v[36:39], v[174:177], v[222:225], v[36:39]
	v_mfma_f32_16x16x32_bf16 v[32:35], v[186:189], v[222:225], v[32:35]
	v_mfma_f32_16x16x32_bf16 v[20:23], v[174:177], v[230:233], v[20:23]
	v_mfma_f32_16x16x32_bf16 v[16:19], v[186:189], v[230:233], v[16:19]
	v_mfma_f32_16x16x32_bf16 v[4:7], v[174:177], v[238:241], v[4:7]
	v_mfma_f32_16x16x32_bf16 v[0:3], v[186:189], v[238:241], v[0:3]
	v_mfma_f32_16x16x32_bf16 v[52:55], v[182:185], v[218:221], v[52:55]
	v_mfma_f32_16x16x32_bf16 v[48:51], v[210:213], v[218:221], v[48:51]
	v_mfma_f32_16x16x32_bf16 v[36:39], v[182:185], v[226:229], v[36:39]
	v_mfma_f32_16x16x32_bf16 v[32:35], v[210:213], v[226:229], v[32:35]
	v_mfma_f32_16x16x32_bf16 v[20:23], v[182:185], v[234:237], v[20:23]
	v_mfma_f32_16x16x32_bf16 v[16:19], v[210:213], v[234:237], v[16:19]
	v_mfma_f32_16x16x32_bf16 v[4:7], v[182:185], v[242:245], v[4:7]
	v_mfma_f32_16x16x32_bf16 v[0:3], v[210:213], v[242:245], v[0:3]
	s_setprio 0
	s_barrier
	s_add_i32 s56, s56, 2
	s_add_u32 s0, s0, 0x100
	s_addc_u32 s1, s1, 0
	s_add_u32 s54, s54, 0x100
	s_addc_u32 s55, s55, 0
	s_cmp_gt_u32 s56, 13

; #define PG8_STAGE(bufoff, gbase, voff) do { _Pragma("unroll") for (int _i = 0; _i < 2; ++_i) \
;         __builtin_amdgcn_global_load_lds((const unsigned*)((const char*)(gbase) + (voff)[_i]), (PG8_LAS unsigned*)(lds + (bufoff) + ldsw + _i * 8192), 16, 0, 0); } while (0)
; #define PG8_LDA(dst, b, h) do { _Pragma("unroll") for (int m = 0; m < 4; ++m) _Pragma("unroll") for (int k = 0; k < 2; ++k) dst[m][k] = *(const PG8_LAS bf16x8*)(lds + PG8_SA(b, h) + aoff + m * 2048 + k * 1024); } while (0)
; #define PG8_LDB(dst, b, h) do { _Pragma("unroll") for (int n = 0; n < 2; ++n) _Pragma("unroll") for (int k = 0; k < 2; ++k) dst[n][k] = *(const PG8_LAS bf16x8*)(lds + PG8_SB(b, h) + boff + n * 2048 + k * 1024); } while (0)
; #define PG8_MMA(ai, bj, At, Bt) do { __builtin_amdgcn_s_setprio(1); _Pragma("unroll") for (int m = 0; m < 4; ++m) _Pragma("unroll") for (int n = 0; n < 2; ++n) _Pragma("unroll") for (int k = 0; k < 2; ++k) \
;         acc[ai][bj][m][n] = __builtin_amdgcn_mfma_f32_16x16x32_bf16(Bt[n][k], At[m][k], acc[ai][bj][m][n], 0, 0, 0); __builtin_amdgcn_s_setprio(0); } while (0)
; #define PG8_BAR __builtin_amdgcn_s_barrier()
; template <class Epi, class Sched, bool ALIGN_EPI = false, bool SP2 = false>
; __device__ __forceinline__ void gemm_phase(PG8_LAS unsigned char* lds, const Gemm g, const Sched& S, const Epi& E) {
;     ...
;         const bool has_next = S.next(ui + 1, nxt);
;         const char* nA = has_next ? (const char*)g.A + (size_t)nxt.pm * tstep : cA; const char* nB = has_next ? (const char*)g.Bt + (size_t)nxt.pn * tstep : cB;
;         for (int t = 0; t < nt; t += 2) {
;             const bool last = (t == nt - 2);
;             const char* a1 = cA + (size_t)(t + 1) * kstep;
;             const char* a2 = last ? nA : cA + (size_t)(t + 2) * kstep; const char* b2 = last ? nB : cB + (size_t)(t + 2) * kstep;
;             const char* a3 = a2 + kstep; const char* b3 = b2 + kstep;
;             if (last && has_next) S.a_ready(nxt);
;             if constexpr (SP2) {
;             PG8_LDB(B0, 0, 0); PG8_LDB(B1, 0, 1); PG8_SCHED; PG8_LDA(At, 0, 0); PG8_STAGE(PG8_SA(1, 1), a1 + hstep, voffA);
;             PG8_WAIT_V(8); PG8_WAIT_L(0); PG8_BAR; PG8_MMA(0, 0, At, B0); PG8_MMA(0, 1, At, B1); PG8_BAR; PG8_SCHED;
;             PG8_LDA(At, 0, 1); PG8_STAGE(PG8_SB(0, 0), b2, voffB); PG8_STAGE(PG8_SB(0, 1), b2 + hstep, voffB); PG8_STAGE(PG8_SA(0, 0), a2, voffA);
.LBB0_445:
	s_ashr_i32 s7, s6, 31
	s_lshl_b64 s[10:11], s[6:7], 19
	s_add_u32 s10, s23, s10
	s_addc_u32 s11, s24, s11
	s_and_b64 s[12:13], s[8:9], exec
	s_cselect_b32 s7, s11, s15
	s_cselect_b32 s49, s10, s14
	s_ashr_i32 s5, s4, 31
	s_lshl_b64 s[12:13], s[4:5], 19
	s_add_u32 s12, s25, s12
	s_addc_u32 s13, s26, s13
	s_and_b64 s[18:19], s[8:9], exec
	s_cselect_b32 s5, s13, s17
	s_cselect_b32 s50, s12, s16
	s_add_u32 s14, s14, 0x40080
	s_addc_u32 s15, s15, 0
	s_add_u32 s51, s16, 0x100
	v_mov_b32_e32 v0, 0
	s_addc_u32 s52, s17, 0
	s_mov_b32 s53, -2
.Lup_peel:
	v_or_b32_e32 v140, 0x10000, v166
	v_add_u32_e32 v162, 0x10400, v166
	ds_read_b128 v[140:143], v140
	ds_read_b128 v[168:171], v162
	v_add_u32_e32 v162, 0x10800, v166
	v_add_u32_e32 v163, 0x10c00, v166
	ds_read_b128 v[172:175], v162
	ds_read_b128 v[176:179], v163
	v_or_b32_e32 v162, 0x14000, v166
	v_add_u32_e32 v163, 0x14400, v166
	ds_read_b128 v[180:183], v162
	ds_read_b128 v[184:187], v163
	v_add_u32_e32 v162, 0x14800, v166
	v_add_u32_e32 v163, 0x14c00, v166
	ds_read_b128 v[188:191], v162
	ds_read_b128 v[210:213], v163
	s_add_u32 s16, s14, 0xfffc0080
	s_addc_u32 s17, s15, -1
	s_cmp_eq_u32 s53, 12
	s_cselect_b32 s19, s7, s17
	s_cselect_b32 s18, s49, s16
	s_cselect_b32 s17, s5, s52
	s_cselect_b32 s16, s50, s51
	s_mov_b32 m0, s43
	v_lshl_add_u64 v[162:163], s[14:15], 0, v[136:137]
	ds_read_b128 v[214:217], v165
	ds_read_b128 v[218:221], v165 offset:1024
	ds_read_b128 v[222:225], v165 offset:2048
	ds_read_b128 v[226:229], v165 offset:3072
	ds_read_b128 v[230:233], v165 offset:4096
	ds_read_b128 v[234:237], v165 offset:5120
	ds_read_b128 v[238:241], v165 offset:6144
	ds_read_b128 v[242:245], v165 offset:7168
	global_load_lds_dwordx4 v[162:163], off
	v_lshl_add_u64 v[162:163], s[14:15], 0, v[138:139]
	s_mov_b32 m0, s44
	s_nop 0
	global_load_lds_dwordx4 v[162:163], off
	s_waitcnt vmcnt(8)
	s_waitcnt lgkmcnt(0)
	s_barrier
	s_setprio 1
	s_waitcnt lgkmcnt(0)
	v_mfma_f32_16x16x32_bf16 v[124:127], v[140:143], v[214:217], 0
	v_mfma_f32_16x16x32_bf16 v[116:119], v[172:175], v[214:217], 0
	v_mfma_f32_16x16x32_bf16 v[108:111], v[140:143], v[222:225], 0
	v_mfma_f32_16x16x32_bf16 v[100:103], v[172:175], v[222:225], 0
	v_mfma_f32_16x16x32_bf16 v[92:95], v[140:143], v[230:233], 0
	v_mfma_f32_16x16x32_bf16 v[84:87], v[172:175], v[230:233], 0
	v_mfma_f32_16x16x32_bf16 v[76:79], v[140:143], v[238:241], 0
	v_mfma_f32_16x16x32_bf16 v[68:71], v[172:175], v[238:241], 0
	v_mfma_f32_16x16x32_bf16 v[124:127], v[168:171], v[218:221], v[124:127]
	v_mfma_f32_16x16x32_bf16 v[116:119], v[176:179], v[218:221], v[116:119]
	v_mfma_f32_16x16x32_bf16 v[108:111], v[168:171], v[226:229], v[108:111]
	v_mfma_f32_16x16x32_bf16 v[100:103], v[176:179], v[226:229], v[100:103]
	v_mfma_f32_16x16x32_bf16 v[92:95], v[168:171], v[234:237], v[92:95]
	v_mfma_f32_16x16x32_bf16 v[84:87], v[176:179], v[234:237], v[84:87]
	v_mfma_f32_16x16x32_bf16 v[76:79], v[168:171], v[242:245], v[76:79]
	v_mfma_f32_16x16x32_bf16 v[68:71], v[176:179], v[242:245], v[68:71]
	s_setprio 0
	s_setprio 1
	v_mfma_f32_16x16x32_bf16 v[120:123], v[180:183], v[214:217], 0
	v_mfma_f32_16x16x32_bf16 v[112:115], v[188:191], v[214:217], 0
	v_mfma_f32_16x16x32_bf16 v[104:107], v[180:183], v[222:225], 0
	v_mfma_f32_16x16x32_bf16 v[96:99], v[188:191], v[222:225], 0
	v_mfma_f32_16x16x32_bf16 v[88:91], v[180:183], v[230:233], 0
	v_mfma_f32_16x16x32_bf16 v[80:83], v[188:191], v[230:233], 0
	v_mfma_f32_16x16x32_bf16 v[72:75], v[180:183], v[238:241], 0
	v_mfma_f32_16x16x32_bf16 v[64:67], v[188:191], v[238:241], 0
	v_mfma_f32_16x16x32_bf16 v[120:123], v[184:187], v[218:221], v[120:123]
	v_mfma_f32_16x16x32_bf16 v[112:115], v[210:213], v[218:221], v[112:115]
	v_mfma_f32_16x16x32_bf16 v[104:107], v[184:187], v[226:229], v[104:107]
	v_mfma_f32_16x16x32_bf16 v[96:99], v[210:213], v[226:229], v[96:99]
	v_mfma_f32_16x16x32_bf16 v[88:91], v[184:187], v[234:237], v[88:91]
	v_mfma_f32_16x16x32_bf16 v[80:83], v[210:213], v[234:237], v[80:83]
	v_mfma_f32_16x16x32_bf16 v[72:75], v[184:187], v[242:245], v[72:75]
	v_mfma_f32_16x16x32_bf16 v[64:67], v[210:213], v[242:245], v[64:67]
	s_setprio 0
	s_barrier
	s_mov_b32 m0, s27
	v_lshl_add_u64 v[162:163], s[16:17], 0, v[132:133]
	s_add_u32 s54, s16, 0x40000
	ds_read_b128 v[214:217], v165 offset:16384
	ds_read_b128 v[218:221], v165 offset:17408
	ds_read_b128 v[222:225], v165 offset:18432
	ds_read_b128 v[226:229], v165 offset:19456
	ds_read_b128 v[230:233], v165 offset:20480
	ds_read_b128 v[234:237], v165 offset:21504
	ds_read_b128 v[238:241], v165 offset:22528
	ds_read_b128 v[242:245], v165 offset:23552
	global_load_lds_dwordx4 v[162:163], off
	v_lshl_add_u64 v[246:247], s[16:17], 0, v[128:129]
	s_mov_b32 m0, s28
	s_addc_u32 s55, s17, 0
	global_load_lds_dwordx4 v[246:247], off
	v_lshl_add_u64 v[248:249], s[54:55], 0, v[132:133]
	s_mov_b32 m0, s29
	v_lshl_add_u64 v[250:251], s[18:19], 0, v[130:131]
	global_load_lds_dwordx4 v[248:249], off
	v_lshl_add_u64 v[248:249], s[54:55], 0, v[128:129]
	s_mov_b32 m0, s30
	s_nop 0
	global_load_lds_dwordx4 v[248:249], off
	v_lshl_add_u64 v[248:249], s[18:19], 0, v[134:135]
	s_mov_b32 m0, s22
	s_nop 0
	global_load_lds_dwordx4 v[248:249], off
	s_mov_b32 m0, s31
	s_nop 0
	global_load_lds_dwordx4 v[250:251], off
	s_waitcnt vmcnt(8)
	s_waitcnt lgkmcnt(0)
	s_barrier
; #define PG8_STAGE(bufoff, gbase, voff) do { _Pragma("unroll") for (int _i = 0; _i < 2; ++_i) \
;         __builtin_amdgcn_global_load_lds((const unsigned*)((const char*)(gbase) + (voff)[_i]), (PG8_LAS unsigned*)(lds + (bufoff) + ldsw + _i * 8192), 16, 0, 0); } while (0)
; #define PG8_LDA(dst, b, h) do { _Pragma("unroll") for (int m = 0; m < 4; ++m) _Pragma("unroll") for (int k = 0; k < 2; ++k) dst[m][k] = *(const PG8_LAS bf16x8*)(lds + PG8_SA(b, h) + aoff + m * 2048 + k * 1024); } while (0)
; #define PG8_LDB(dst, b, h) do { _Pragma("unroll") for (int n = 0; n < 2; ++n) _Pragma("unroll") for (int k = 0; k < 2; ++k) dst[n][k] = *(const PG8_LAS bf16x8*)(lds + PG8_SB(b, h) + boff + n * 2048 + k * 1024); } while (0)
; #define PG8_MMA(ai, bj, At, Bt) do { __builtin_amdgcn_s_setprio(1); _Pragma("unroll") for (int m = 0; m < 4; ++m) _Pragma("unroll") for (int n = 0; n < 2; ++n) _Pragma("unroll") for (int k = 0; k < 2; ++k) \
;         acc[ai][bj][m][n] = __builtin_amdgcn_mfma_f32_16x16x32_bf16(Bt[n][k], At[m][k], acc[ai][bj][m][n], 0, 0, 0); __builtin_amdgcn_s_setprio(0); } while (0)
; #define PG8_WAIT_V(n) asm volatile("s_waitcnt vmcnt(" #n ")" ::: "memory")
; #define PG8_WAIT_L(n) asm volatile("s_waitcnt lgkmcnt(" #n ")" ::: "memory")
; #define PG8_BAR __builtin_amdgcn_s_barrier()
; #define PG8_SCHED __builtin_amdgcn_sched_barrier(0)
; template <class Epi, class Sched, bool ALIGN_EPI = false, bool SP2 = false>
; __device__ __forceinline__ void gemm_phase(PG8_LAS unsigned char* lds, const Gemm g, const Sched& S, const Epi& E) {
;     ...
;             PG8_WAIT_V(8); PG8_WAIT_L(0); PG8_BAR; PG8_MMA(1, 0, At, B0); PG8_MMA(1, 1, At, B1); PG8_BAR; PG8_SCHED;
;             PG8_LDB(B0, 1, 0); PG8_LDB(B1, 1, 1); PG8_SCHED; PG8_LDA(At, 1, 0); PG8_STAGE(PG8_SA(0, 1), a2 + hstep, voffA);
;             PG8_WAIT_V(8); PG8_WAIT_L(0); PG8_BAR; PG8_MMA(0, 0, At, B0); PG8_MMA(0, 1, At, B1); PG8_BAR; PG8_SCHED;
	s_setprio 1
	s_waitcnt lgkmcnt(0)
	v_mfma_f32_16x16x32_bf16 v[60:63], v[140:143], v[214:217], 0
	v_mfma_f32_16x16x32_bf16 v[52:55], v[172:175], v[214:217], 0
	v_mfma_f32_16x16x32_bf16 v[44:47], v[140:143], v[222:225], 0
	v_mfma_f32_16x16x32_bf16 v[36:39], v[172:175], v[222:225], 0
	v_mfma_f32_16x16x32_bf16 v[28:31], v[140:143], v[230:233], 0
	v_mfma_f32_16x16x32_bf16 v[20:23], v[172:175], v[230:233], 0
	v_mfma_f32_16x16x32_bf16 v[12:15], v[140:143], v[238:241], 0
	v_mfma_f32_16x16x32_bf16 v[4:7], v[172:175], v[238:241], 0
	v_mfma_f32_16x16x32_bf16 v[60:63], v[168:171], v[218:221], v[60:63]
	v_mfma_f32_16x16x32_bf16 v[52:55], v[176:179], v[218:221], v[52:55]
	v_mfma_f32_16x16x32_bf16 v[44:47], v[168:171], v[226:229], v[44:47]
	v_mfma_f32_16x16x32_bf16 v[36:39], v[176:179], v[226:229], v[36:39]
	v_mfma_f32_16x16x32_bf16 v[28:31], v[168:171], v[234:237], v[28:31]
	v_mfma_f32_16x16x32_bf16 v[20:23], v[176:179], v[234:237], v[20:23]
	v_mfma_f32_16x16x32_bf16 v[12:15], v[168:171], v[242:245], v[12:15]
	v_mfma_f32_16x16x32_bf16 v[4:7], v[176:179], v[242:245], v[4:7]
	s_setprio 0
	s_setprio 1
	v_mfma_f32_16x16x32_bf16 v[56:59], v[180:183], v[214:217], 0
	v_mfma_f32_16x16x32_bf16 v[48:51], v[188:191], v[214:217], 0
	v_mfma_f32_16x16x32_bf16 v[40:43], v[180:183], v[222:225], 0
	v_mfma_f32_16x16x32_bf16 v[32:35], v[188:191], v[222:225], 0
	v_mfma_f32_16x16x32_bf16 v[24:27], v[180:183], v[230:233], 0
	v_mfma_f32_16x16x32_bf16 v[16:19], v[188:191], v[230:233], 0
	v_mfma_f32_16x16x32_bf16 v[8:11], v[180:183], v[238:241], 0
	v_mfma_f32_16x16x32_bf16 v[0:3], v[188:191], v[238:241], 0
	v_mfma_f32_16x16x32_bf16 v[56:59], v[184:187], v[218:221], v[56:59]
	v_mfma_f32_16x16x32_bf16 v[48:51], v[210:213], v[218:221], v[48:51]
	v_mfma_f32_16x16x32_bf16 v[40:43], v[184:187], v[226:229], v[40:43]
	v_mfma_f32_16x16x32_bf16 v[32:35], v[210:213], v[226:229], v[32:35]
	v_mfma_f32_16x16x32_bf16 v[24:27], v[184:187], v[234:237], v[24:27]
	v_mfma_f32_16x16x32_bf16 v[16:19], v[210:213], v[234:237], v[16:19]
	v_mfma_f32_16x16x32_bf16 v[8:11], v[184:187], v[242:245], v[8:11]
	v_mfma_f32_16x16x32_bf16 v[0:3], v[210:213], v[242:245], v[0:3]
	s_setprio 0
	s_barrier
	v_or_b32_e32 v140, 0x18000, v166
	v_add_u32_e32 v167, 0x18400, v166
	ds_read_b128 v[140:143], v140
	ds_read_b128 v[168:171], v167
	v_add_u32_e32 v167, 0x18800, v166
	v_add_u32_e32 v176, 0x18c00, v166
	ds_read_b128 v[172:175], v167
	ds_read_b128 v[176:179], v176
	v_or_b32_e32 v167, 0x1c000, v166
	v_add_u32_e32 v184, 0x1c400, v166
	ds_read_b128 v[180:183], v167
	ds_read_b128 v[184:187], v184
	v_add_u32_e32 v167, 0x1c800, v166
	v_add_u32_e32 v208, 0x1cc00, v166
	ds_read_b128 v[188:191], v167
	ds_read_b128 v[210:213], v208
	s_add_u32 s18, s18, 0x40000
	s_addc_u32 s19, s19, 0
	s_mov_b32 m0, s33
	v_lshl_add_u64 v[208:209], s[18:19], 0, v[134:135]
	ds_read_b128 v[214:217], v165 offset:32768
	ds_read_b128 v[218:221], v165 offset:33792
	ds_read_b128 v[222:225], v165 offset:34816
	ds_read_b128 v[226:229], v165 offset:35840
	ds_read_b128 v[230:233], v165 offset:36864
	ds_read_b128 v[234:237], v165 offset:37888
	ds_read_b128 v[238:241], v165 offset:38912
	ds_read_b128 v[242:245], v165 offset:39936
	global_load_lds_dwordx4 v[208:209], off
	v_lshl_add_u64 v[208:209], s[18:19], 0, v[130:131]
	s_mov_b32 m0, s34
	s_nop 0
	global_load_lds_dwordx4 v[208:209], off
	s_waitcnt vmcnt(8)
	s_waitcnt lgkmcnt(0)
	s_barrier
	s_setprio 1
	s_waitcnt lgkmcnt(0)
	v_mfma_f32_16x16x32_bf16 v[124:127], v[140:143], v[214:217], v[124:127]
	v_mfma_f32_16x16x32_bf16 v[116:119], v[172:175], v[214:217], v[116:119]
	v_mfma_f32_16x16x32_bf16 v[108:111], v[140:143], v[222:225], v[108:111]
	v_mfma_f32_16x16x32_bf16 v[100:103], v[172:175], v[222:225], v[100:103]
	v_mfma_f32_16x16x32_bf16 v[92:95], v[140:143], v[230:233], v[92:95]
	v_mfma_f32_16x16x32_bf16 v[84:87], v[172:175], v[230:233], v[84:87]
	v_mfma_f32_16x16x32_bf16 v[76:79], v[140:143], v[238:241], v[76:79]
	v_mfma_f32_16x16x32_bf16 v[68:71], v[172:175], v[238:241], v[68:71]
	v_mfma_f32_16x16x32_bf16 v[124:127], v[168:171], v[218:221], v[124:127]
	v_mfma_f32_16x16x32_bf16 v[116:119], v[176:179], v[218:221], v[116:119]
	v_mfma_f32_16x16x32_bf16 v[108:111], v[168:171], v[226:229], v[108:111]
	v_mfma_f32_16x16x32_bf16 v[100:103], v[176:179], v[226:229], v[100:103]
	v_mfma_f32_16x16x32_bf16 v[92:95], v[168:171], v[234:237], v[92:95]
	v_mfma_f32_16x16x32_bf16 v[84:87], v[176:179], v[234:237], v[84:87]
	v_mfma_f32_16x16x32_bf16 v[76:79], v[168:171], v[242:245], v[76:79]
	v_mfma_f32_16x16x32_bf16 v[68:71], v[176:179], v[242:245], v[68:71]
	s_setprio 0
	s_setprio 1
	v_mfma_f32_16x16x32_bf16 v[120:123], v[180:183], v[214:217], v[120:123]
	v_mfma_f32_16x16x32_bf16 v[112:115], v[188:191], v[214:217], v[112:115]
	v_mfma_f32_16x16x32_bf16 v[104:107], v[180:183], v[222:225], v[104:107]
	v_mfma_f32_16x16x32_bf16 v[96:99], v[188:191], v[222:225], v[96:99]
	v_mfma_f32_16x16x32_bf16 v[88:91], v[180:183], v[230:233], v[88:91]
	v_mfma_f32_16x16x32_bf16 v[80:83], v[188:191], v[230:233], v[80:83]
	v_mfma_f32_16x16x32_bf16 v[72:75], v[180:183], v[238:241], v[72:75]
	v_mfma_f32_16x16x32_bf16 v[64:67], v[188:191], v[238:241], v[64:67]
	v_mfma_f32_16x16x32_bf16 v[120:123], v[184:187], v[218:221], v[120:123]
	v_mfma_f32_16x16x32_bf16 v[112:115], v[210:213], v[218:221], v[112:115]
	v_mfma_f32_16x16x32_bf16 v[104:107], v[184:187], v[226:229], v[104:107]
	v_mfma_f32_16x16x32_bf16 v[96:99], v[210:213], v[226:229], v[96:99]
	v_mfma_f32_16x16x32_bf16 v[88:91], v[184:187], v[234:237], v[88:91]
	v_mfma_f32_16x16x32_bf16 v[80:83], v[210:213], v[234:237], v[80:83]
	v_mfma_f32_16x16x32_bf16 v[72:75], v[184:187], v[242:245], v[72:75]
	v_mfma_f32_16x16x32_bf16 v[64:67], v[210:213], v[242:245], v[64:67]
	s_setprio 0
	s_barrier
; #define PG8_STAGE(bufoff, gbase, voff) do { _Pragma("unroll") for (int _i = 0; _i < 2; ++_i) \
;         __builtin_amdgcn_global_load_lds((const unsigned*)((const char*)(gbase) + (voff)[_i]), (PG8_LAS unsigned*)(lds + (bufoff) + ldsw + _i * 8192), 16, 0, 0); } while (0)
; #define PG8_LDA(dst, b, h) do { _Pragma("unroll") for (int m = 0; m < 4; ++m) _Pragma("unroll") for (int k = 0; k < 2; ++k) dst[m][k] = *(const PG8_LAS bf16x8*)(lds + PG8_SA(b, h) + aoff + m * 2048 + k * 1024); } while (0)
; #define PG8_MMA(ai, bj, At, Bt) do { __builtin_amdgcn_s_setprio(1); _Pragma("unroll") for (int m = 0; m < 4; ++m) _Pragma("unroll") for (int n = 0; n < 2; ++n) _Pragma("unroll") for (int k = 0; k < 2; ++k) \
;         acc[ai][bj][m][n] = __builtin_amdgcn_mfma_f32_16x16x32_bf16(Bt[n][k], At[m][k], acc[ai][bj][m][n], 0, 0, 0); __builtin_amdgcn_s_setprio(0); } while (0)
; #define PG8_WAIT_V(n) asm volatile("s_waitcnt vmcnt(" #n ")" ::: "memory")
; #define PG8_WAIT_L(n) asm volatile("s_waitcnt lgkmcnt(" #n ")" ::: "memory")
; #define PG8_BAR __builtin_amdgcn_s_barrier()
; #define PG8_SCHED __builtin_amdgcn_sched_barrier(0)
; template <class Epi, class Sched, bool ALIGN_EPI = false, bool SP2 = false>
; __device__ __forceinline__ void gemm_phase(PG8_LAS unsigned char* lds, const Gemm g, const Sched& S, const Epi& E) {
;     ...
;         for (int t = 0; t < nt; t += 2) {
;             const bool last = (t == nt - 2);
;             const char* a1 = cA + (size_t)(t + 1) * kstep;
;             const char* a2 = last ? nA : cA + (size_t)(t + 2) * kstep; const char* b2 = last ? nB : cB + (size_t)(t + 2) * kstep;
;             const char* a3 = a2 + kstep; const char* b3 = b2 + kstep;
;     ...
;             PG8_LDA(At, 1, 1); PG8_STAGE(PG8_SB(1, 0), b3, voffB); PG8_STAGE(PG8_SB(1, 1), b3 + hstep, voffB); PG8_STAGE(PG8_SA(1, 0), a3, voffA);
;             PG8_WAIT_V(8); PG8_WAIT_L(0); PG8_BAR; PG8_MMA(1, 0, At, B0); PG8_MMA(1, 1, At, B1); PG8_BAR; PG8_SCHED;
	s_mov_b32 m0, s37
	v_lshl_add_u64 v[162:163], v[162:163], 0, s[94:95]
	s_add_u32 s16, s16, 0x40080
	ds_read_b128 v[214:217], v165 offset:49152
	ds_read_b128 v[218:221], v165 offset:50176
	ds_read_b128 v[222:225], v165 offset:51200
	ds_read_b128 v[226:229], v165 offset:52224
	ds_read_b128 v[230:233], v165 offset:53248
	ds_read_b128 v[234:237], v165 offset:54272
	ds_read_b128 v[238:241], v165 offset:55296
	ds_read_b128 v[242:245], v165 offset:56320
	global_load_lds_dwordx4 v[162:163], off
	v_lshl_add_u64 v[162:163], v[246:247], 0, s[94:95]
	s_mov_b32 m0, s38
	s_addc_u32 s17, s17, 0
	global_load_lds_dwordx4 v[162:163], off
	v_lshl_add_u64 v[162:163], s[16:17], 0, v[132:133]
	s_mov_b32 m0, s41
	s_nop 0
	global_load_lds_dwordx4 v[162:163], off
	v_lshl_add_u64 v[162:163], s[16:17], 0, v[128:129]
	s_mov_b32 m0, s42
	s_nop 0
	global_load_lds_dwordx4 v[162:163], off
	v_lshl_add_u64 v[162:163], v[248:249], 0, s[94:95]
	s_mov_b32 m0, s39
	s_nop 0
	global_load_lds_dwordx4 v[162:163], off
	v_lshl_add_u64 v[162:163], v[250:251], 0, s[94:95]
	s_mov_b32 m0, s40
	s_nop 0
	global_load_lds_dwordx4 v[162:163], off
	s_waitcnt vmcnt(8)
	s_waitcnt lgkmcnt(0)
	s_barrier
	s_setprio 1
	s_waitcnt lgkmcnt(0)
	v_mfma_f32_16x16x32_bf16 v[60:63], v[140:143], v[214:217], v[60:63]
	v_mfma_f32_16x16x32_bf16 v[52:55], v[172:175], v[214:217], v[52:55]
	v_mfma_f32_16x16x32_bf16 v[44:47], v[140:143], v[222:225], v[44:47]
	v_mfma_f32_16x16x32_bf16 v[36:39], v[172:175], v[222:225], v[36:39]
	v_mfma_f32_16x16x32_bf16 v[28:31], v[140:143], v[230:233], v[28:31]
	v_mfma_f32_16x16x32_bf16 v[20:23], v[172:175], v[230:233], v[20:23]
	v_mfma_f32_16x16x32_bf16 v[12:15], v[140:143], v[238:241], v[12:15]
	v_mfma_f32_16x16x32_bf16 v[4:7], v[172:175], v[238:241], v[4:7]
	v_mfma_f32_16x16x32_bf16 v[60:63], v[168:171], v[218:221], v[60:63]
	v_mfma_f32_16x16x32_bf16 v[52:55], v[176:179], v[218:221], v[52:55]
	v_mfma_f32_16x16x32_bf16 v[44:47], v[168:171], v[226:229], v[44:47]
	v_mfma_f32_16x16x32_bf16 v[36:39], v[176:179], v[226:229], v[36:39]
	v_mfma_f32_16x16x32_bf16 v[28:31], v[168:171], v[234:237], v[28:31]
	v_mfma_f32_16x16x32_bf16 v[20:23], v[176:179], v[234:237], v[20:23]
	v_mfma_f32_16x16x32_bf16 v[12:15], v[168:171], v[242:245], v[12:15]
	v_mfma_f32_16x16x32_bf16 v[4:7], v[176:179], v[242:245], v[4:7]
	s_setprio 0
	s_setprio 1
	v_mfma_f32_16x16x32_bf16 v[56:59], v[180:183], v[214:217], v[56:59]
	v_mfma_f32_16x16x32_bf16 v[48:51], v[188:191], v[214:217], v[48:51]
	v_mfma_f32_16x16x32_bf16 v[40:43], v[180:183], v[222:225], v[40:43]
	v_mfma_f32_16x16x32_bf16 v[32:35], v[188:191], v[222:225], v[32:35]
	v_mfma_f32_16x16x32_bf16 v[24:27], v[180:183], v[230:233], v[24:27]
	v_mfma_f32_16x16x32_bf16 v[16:19], v[188:191], v[230:233], v[16:19]
	v_mfma_f32_16x16x32_bf16 v[8:11], v[180:183], v[238:241], v[8:11]
	v_mfma_f32_16x16x32_bf16 v[0:3], v[188:191], v[238:241], v[0:3]
	v_mfma_f32_16x16x32_bf16 v[56:59], v[184:187], v[218:221], v[56:59]
	v_mfma_f32_16x16x32_bf16 v[48:51], v[210:213], v[218:221], v[48:51]
	v_mfma_f32_16x16x32_bf16 v[40:43], v[184:187], v[226:229], v[40:43]
	v_mfma_f32_16x16x32_bf16 v[32:35], v[210:213], v[226:229], v[32:35]
	v_mfma_f32_16x16x32_bf16 v[24:27], v[184:187], v[234:237], v[24:27]
	v_mfma_f32_16x16x32_bf16 v[16:19], v[210:213], v[234:237], v[16:19]
	v_mfma_f32_16x16x32_bf16 v[8:11], v[184:187], v[242:245], v[8:11]
	v_mfma_f32_16x16x32_bf16 v[0:3], v[210:213], v[242:245], v[0:3]
	s_setprio 0
	s_barrier
	s_add_i32 s53, s53, 2
	s_add_u32 s14, s14, 0x100
	s_addc_u32 s15, s15, 0
	s_add_u32 s51, s51, 0x100
	s_addc_u32 s52, s52, 0
	s_cmp_gt_u32 s53, 13

; #define PG8_STAGE(bufoff, gbase, voff) do { _Pragma("unroll") for (int _i = 0; _i < 2; ++_i) \
;         __builtin_amdgcn_global_load_lds((const unsigned*)((const char*)(gbase) + (voff)[_i]), (PG8_LAS unsigned*)(lds + (bufoff) + ldsw + _i * 8192), 16, 0, 0); } while (0)
; #define PG8_LDA(dst, b, h) do { _Pragma("unroll") for (int m = 0; m < 4; ++m) _Pragma("unroll") for (int k = 0; k < 2; ++k) dst[m][k] = *(const PG8_LAS bf16x8*)(lds + PG8_SA(b, h) + aoff + m * 2048 + k * 1024); } while (0)
; #define PG8_LDB(dst, b, h) do { _Pragma("unroll") for (int n = 0; n < 2; ++n) _Pragma("unroll") for (int k = 0; k < 2; ++k) dst[n][k] = *(const PG8_LAS bf16x8*)(lds + PG8_SB(b, h) + boff + n * 2048 + k * 1024); } while (0)
; #define PG8_MMA(ai, bj, At, Bt) do { __builtin_amdgcn_s_setprio(1); _Pragma("unroll") for (int m = 0; m < 4; ++m) _Pragma("unroll") for (int n = 0; n < 2; ++n) _Pragma("unroll") for (int k = 0; k < 2; ++k) \
;         acc[ai][bj][m][n] = __builtin_amdgcn_mfma_f32_16x16x32_bf16(Bt[n][k], At[m][k], acc[ai][bj][m][n], 0, 0, 0); __builtin_amdgcn_s_setprio(0); } while (0)
; #define PG8_WAIT_V(n) asm volatile("s_waitcnt vmcnt(" #n ")" ::: "memory")
; #define PG8_WAIT_L(n) asm volatile("s_waitcnt lgkmcnt(" #n ")" ::: "memory")
; #define PG8_BAR __builtin_amdgcn_s_barrier()
; #define PG8_SCHED __builtin_amdgcn_sched_barrier(0)
; template <class Epi, class Sched, bool ALIGN_EPI = false, bool SP2 = false>
; __device__ __forceinline__ void gemm_phase(PG8_LAS unsigned char* lds, const Gemm g, const Sched& S, const Epi& E) {
;     ...
;             PG8_LDB(B0, 0, 0); PG8_LDB(B1, 0, 1); PG8_SCHED; PG8_LDA(At, 0, 0); PG8_STAGE(PG8_SA(1, 1), a1 + hstep, voffA);
;             PG8_WAIT_V(8); PG8_WAIT_L(0); PG8_BAR; PG8_MMA(0, 0, At, B0); PG8_MMA(0, 1, At, B1); PG8_BAR; PG8_SCHED;
;             PG8_LDA(At, 0, 1); PG8_STAGE(PG8_SB(0, 0), b2, voffB); PG8_STAGE(PG8_SB(0, 1), b2 + hstep, voffB); PG8_STAGE(PG8_SA(0, 0), a2, voffA);
.Ldn_peel:
	v_or_b32_e32 v128, 0x10000, v182
	v_add_u32_e32 v132, 0x10400, v182
	v_add_u32_e32 v136, 0x10800, v182
	v_add_u32_e32 v140, 0x10c00, v182
	v_or_b32_e32 v174, 0x14000, v182
	v_add_u32_e32 v178, 0x14400, v182
	ds_read_b128 v[128:131], v128
	ds_read_b128 v[132:135], v132
	ds_read_b128 v[136:139], v136
	ds_read_b128 v[140:143], v140
	ds_read_b128 v[174:177], v174
	ds_read_b128 v[184:187], v178
	v_add_u32_e32 v178, 0x14800, v182
	v_add_u32_e32 v179, 0x14c00, v182
	ds_read_b128 v[188:191], v178
	ds_read_b128 v[210:213], v179
	s_add_u32 s2, s0, 0x100
	s_addc_u32 s3, s1, 0
	s_cmp_eq_u32 s13, 40
	s_cselect_b32 s7, s27, s3
	s_cselect_b32 s6, s26, s2
	s_cselect_b32 s5, s37, s11
	s_cselect_b32 s4, s36, s10
	v_lshl_add_u64 v[178:179], s[0:1], 0, v[170:171]
	s_add_i32 m0, s29, 0xc000
	ds_read_b128 v[214:217], v181
	ds_read_b128 v[218:221], v181 offset:1024
	ds_read_b128 v[222:225], v181 offset:2048
	ds_read_b128 v[226:229], v181 offset:3072
	ds_read_b128 v[230:233], v181 offset:4096
	ds_read_b128 v[234:237], v181 offset:5120
	ds_read_b128 v[238:241], v181 offset:6144
	ds_read_b128 v[242:245], v181 offset:7168
	global_load_lds_dwordx4 v[178:179], off
	v_lshl_add_u64 v[178:179], s[0:1], 0, v[172:173]
	s_add_i32 m0, s29, 0xe000
	s_nop 0
	global_load_lds_dwordx4 v[178:179], off
	s_waitcnt vmcnt(8)
	s_waitcnt lgkmcnt(0)
	s_barrier
	s_setprio 1
	s_waitcnt lgkmcnt(0)
	v_mfma_f32_16x16x32_bf16 v[124:127], v[128:131], v[214:217], 0
	v_mfma_f32_16x16x32_bf16 v[120:123], v[136:139], v[214:217], 0
	v_mfma_f32_16x16x32_bf16 v[108:111], v[128:131], v[222:225], 0
	v_mfma_f32_16x16x32_bf16 v[104:107], v[136:139], v[222:225], 0
	v_mfma_f32_16x16x32_bf16 v[92:95], v[128:131], v[230:233], 0
	v_mfma_f32_16x16x32_bf16 v[88:91], v[136:139], v[230:233], 0
	v_mfma_f32_16x16x32_bf16 v[76:79], v[128:131], v[238:241], 0
	v_mfma_f32_16x16x32_bf16 v[72:75], v[136:139], v[238:241], 0
	v_mfma_f32_16x16x32_bf16 v[124:127], v[132:135], v[218:221], v[124:127]
	v_mfma_f32_16x16x32_bf16 v[120:123], v[140:143], v[218:221], v[120:123]
	v_mfma_f32_16x16x32_bf16 v[108:111], v[132:135], v[226:229], v[108:111]
	v_mfma_f32_16x16x32_bf16 v[104:107], v[140:143], v[226:229], v[104:107]
	v_mfma_f32_16x16x32_bf16 v[92:95], v[132:135], v[234:237], v[92:95]
	v_mfma_f32_16x16x32_bf16 v[88:91], v[140:143], v[234:237], v[88:91]
	v_mfma_f32_16x16x32_bf16 v[76:79], v[132:135], v[242:245], v[76:79]
	v_mfma_f32_16x16x32_bf16 v[72:75], v[140:143], v[242:245], v[72:75]
	s_setprio 0
	s_setprio 1
	v_mfma_f32_16x16x32_bf16 v[116:119], v[174:177], v[214:217], 0
	v_mfma_f32_16x16x32_bf16 v[112:115], v[188:191], v[214:217], 0
	v_mfma_f32_16x16x32_bf16 v[100:103], v[174:177], v[222:225], 0
	v_mfma_f32_16x16x32_bf16 v[96:99], v[188:191], v[222:225], 0
	v_mfma_f32_16x16x32_bf16 v[84:87], v[174:177], v[230:233], 0
	v_mfma_f32_16x16x32_bf16 v[80:83], v[188:191], v[230:233], 0
	v_mfma_f32_16x16x32_bf16 v[68:71], v[174:177], v[238:241], 0
	v_mfma_f32_16x16x32_bf16 v[64:67], v[188:191], v[238:241], 0
	v_mfma_f32_16x16x32_bf16 v[116:119], v[184:187], v[218:221], v[116:119]
	v_mfma_f32_16x16x32_bf16 v[112:115], v[210:213], v[218:221], v[112:115]
	v_mfma_f32_16x16x32_bf16 v[100:103], v[184:187], v[226:229], v[100:103]
	v_mfma_f32_16x16x32_bf16 v[96:99], v[210:213], v[226:229], v[96:99]
	v_mfma_f32_16x16x32_bf16 v[84:87], v[184:187], v[234:237], v[84:87]
	v_mfma_f32_16x16x32_bf16 v[80:83], v[210:213], v[234:237], v[80:83]
	v_mfma_f32_16x16x32_bf16 v[68:71], v[184:187], v[242:245], v[68:71]
	v_mfma_f32_16x16x32_bf16 v[64:67], v[210:213], v[242:245], v[64:67]
	s_setprio 0
	s_barrier
	s_mov_b32 m0, s35
	v_lshl_add_u64 v[178:179], s[4:5], 0, v[166:167]
	s_add_u32 s0, s4, 0xb0000
	ds_read_b128 v[214:217], v181 offset:16384
	ds_read_b128 v[218:221], v181 offset:17408
	ds_read_b128 v[222:225], v181 offset:18432
	ds_read_b128 v[226:229], v181 offset:19456
	ds_read_b128 v[230:233], v181 offset:20480
	ds_read_b128 v[234:237], v181 offset:21504
	ds_read_b128 v[238:241], v181 offset:22528
	ds_read_b128 v[242:245], v181 offset:23552
	global_load_lds_dwordx4 v[178:179], off
	v_lshl_add_u64 v[208:209], s[4:5], 0, v[162:163]
	s_mov_b32 m0, s38
	s_addc_u32 s1, s5, 0
	global_load_lds_dwordx4 v[208:209], off
	v_lshl_add_u64 v[246:247], s[0:1], 0, v[166:167]
	s_mov_b32 m0, s39
	v_lshl_add_u64 v[248:249], s[6:7], 0, v[164:165]
	global_load_lds_dwordx4 v[246:247], off
	v_lshl_add_u64 v[246:247], s[0:1], 0, v[162:163]
	s_mov_b32 m0, s40
	s_nop 0
	global_load_lds_dwordx4 v[246:247], off
	v_lshl_add_u64 v[246:247], s[6:7], 0, v[168:169]
	s_mov_b32 m0, s29
	s_nop 0
	global_load_lds_dwordx4 v[246:247], off
	s_mov_b32 m0, s41
	s_nop 0
	global_load_lds_dwordx4 v[248:249], off
	s_waitcnt vmcnt(8)
	s_waitcnt lgkmcnt(0)
	s_barrier
; #define PG8_STAGE(bufoff, gbase, voff) do { _Pragma("unroll") for (int _i = 0; _i < 2; ++_i) \
;         __builtin_amdgcn_global_load_lds((const unsigned*)((const char*)(gbase) + (voff)[_i]), (PG8_LAS unsigned*)(lds + (bufoff) + ldsw + _i * 8192), 16, 0, 0); } while (0)
; #define PG8_LDA(dst, b, h) do { _Pragma("unroll") for (int m = 0; m < 4; ++m) _Pragma("unroll") for (int k = 0; k < 2; ++k) dst[m][k] = *(const PG8_LAS bf16x8*)(lds + PG8_SA(b, h) + aoff + m * 2048 + k * 1024); } while (0)
; #define PG8_LDB(dst, b, h) do { _Pragma("unroll") for (int n = 0; n < 2; ++n) _Pragma("unroll") for (int k = 0; k < 2; ++k) dst[n][k] = *(const PG8_LAS bf16x8*)(lds + PG8_SB(b, h) + boff + n * 2048 + k * 1024); } while (0)
; #define PG8_MMA(ai, bj, At, Bt) do { __builtin_amdgcn_s_setprio(1); _Pragma("unroll") for (int m = 0; m < 4; ++m) _Pragma("unroll") for (int n = 0; n < 2; ++n) _Pragma("unroll") for (int k = 0; k < 2; ++k) \
;         acc[ai][bj][m][n] = __builtin_amdgcn_mfma_f32_16x16x32_bf16(Bt[n][k], At[m][k], acc[ai][bj][m][n], 0, 0, 0); __builtin_amdgcn_s_setprio(0); } while (0)
; #define PG8_WAIT_V(n) asm volatile("s_waitcnt vmcnt(" #n ")" ::: "memory")
; #define PG8_WAIT_L(n) asm volatile("s_waitcnt lgkmcnt(" #n ")" ::: "memory")
; #define PG8_BAR __builtin_amdgcn_s_barrier()
; #define PG8_SCHED __builtin_amdgcn_sched_barrier(0)
; template <class Epi, class Sched, bool ALIGN_EPI = false, bool SP2 = false>
; __device__ __forceinline__ void gemm_phase(PG8_LAS unsigned char* lds, const Gemm g, const Sched& S, const Epi& E) {
;     ...
;             PG8_WAIT_V(8); PG8_WAIT_L(0); PG8_BAR; PG8_MMA(1, 0, At, B0); PG8_MMA(1, 1, At, B1); PG8_BAR; PG8_SCHED;
;             PG8_LDB(B0, 1, 0); PG8_LDB(B1, 1, 1); PG8_SCHED; PG8_LDA(At, 1, 0); PG8_STAGE(PG8_SA(0, 1), a2 + hstep, voffA);
;             PG8_WAIT_V(8); PG8_WAIT_L(0); PG8_BAR; PG8_MMA(0, 0, At, B0); PG8_MMA(0, 1, At, B1); PG8_BAR; PG8_SCHED;
	s_setprio 1
	s_waitcnt lgkmcnt(0)
	v_mfma_f32_16x16x32_bf16 v[60:63], v[128:131], v[214:217], 0
	v_mfma_f32_16x16x32_bf16 v[56:59], v[136:139], v[214:217], 0
	v_mfma_f32_16x16x32_bf16 v[44:47], v[128:131], v[222:225], 0
	v_mfma_f32_16x16x32_bf16 v[40:43], v[136:139], v[222:225], 0
	v_mfma_f32_16x16x32_bf16 v[28:31], v[128:131], v[230:233], 0
	v_mfma_f32_16x16x32_bf16 v[24:27], v[136:139], v[230:233], 0
	v_mfma_f32_16x16x32_bf16 v[12:15], v[128:131], v[238:241], 0
	v_mfma_f32_16x16x32_bf16 v[8:11], v[136:139], v[238:241], 0
	v_mfma_f32_16x16x32_bf16 v[60:63], v[132:135], v[218:221], v[60:63]
	v_mfma_f32_16x16x32_bf16 v[56:59], v[140:143], v[218:221], v[56:59]
	v_mfma_f32_16x16x32_bf16 v[44:47], v[132:135], v[226:229], v[44:47]
	v_mfma_f32_16x16x32_bf16 v[40:43], v[140:143], v[226:229], v[40:43]
	v_mfma_f32_16x16x32_bf16 v[28:31], v[132:135], v[234:237], v[28:31]
	v_mfma_f32_16x16x32_bf16 v[24:27], v[140:143], v[234:237], v[24:27]
	v_mfma_f32_16x16x32_bf16 v[12:15], v[132:135], v[242:245], v[12:15]
	v_mfma_f32_16x16x32_bf16 v[8:11], v[140:143], v[242:245], v[8:11]
	s_setprio 0
	s_setprio 1
	v_mfma_f32_16x16x32_bf16 v[52:55], v[174:177], v[214:217], 0
	v_mfma_f32_16x16x32_bf16 v[48:51], v[188:191], v[214:217], 0
	v_mfma_f32_16x16x32_bf16 v[36:39], v[174:177], v[222:225], 0
	v_mfma_f32_16x16x32_bf16 v[32:35], v[188:191], v[222:225], 0
	v_mfma_f32_16x16x32_bf16 v[20:23], v[174:177], v[230:233], 0
	v_mfma_f32_16x16x32_bf16 v[16:19], v[188:191], v[230:233], 0
	v_mfma_f32_16x16x32_bf16 v[4:7], v[174:177], v[238:241], 0
	v_mfma_f32_16x16x32_bf16 v[0:3], v[188:191], v[238:241], 0
	v_mfma_f32_16x16x32_bf16 v[52:55], v[184:187], v[218:221], v[52:55]
	v_mfma_f32_16x16x32_bf16 v[48:51], v[210:213], v[218:221], v[48:51]
	v_mfma_f32_16x16x32_bf16 v[36:39], v[184:187], v[226:229], v[36:39]
	v_mfma_f32_16x16x32_bf16 v[32:35], v[210:213], v[226:229], v[32:35]
	v_mfma_f32_16x16x32_bf16 v[20:23], v[184:187], v[234:237], v[20:23]
	v_mfma_f32_16x16x32_bf16 v[16:19], v[210:213], v[234:237], v[16:19]
	v_mfma_f32_16x16x32_bf16 v[4:7], v[184:187], v[242:245], v[4:7]
	v_mfma_f32_16x16x32_bf16 v[0:3], v[210:213], v[242:245], v[0:3]
	s_setprio 0
	s_barrier
	v_or_b32_e32 v128, 0x18000, v182
	v_add_u32_e32 v132, 0x18400, v182
	v_add_u32_e32 v136, 0x18800, v182
	v_add_u32_e32 v140, 0x18c00, v182
	v_or_b32_e32 v174, 0x1c000, v182
	v_add_u32_e32 v183, 0x1c400, v182
	ds_read_b128 v[128:131], v128
	ds_read_b128 v[132:135], v132
	ds_read_b128 v[136:139], v136
	ds_read_b128 v[140:143], v140
	ds_read_b128 v[174:177], v174
	ds_read_b128 v[184:187], v183
	v_add_u32_e32 v183, 0x1c800, v182
	v_add_u32_e32 v210, 0x1cc00, v182
	ds_read_b128 v[188:191], v183
	ds_read_b128 v[210:213], v210
	s_add_u32 s0, s6, 0xb0000
	s_addc_u32 s1, s7, 0
	s_mov_b32 m0, s42
	v_lshl_add_u64 v[250:251], s[0:1], 0, v[168:169]
	ds_read_b128 v[214:217], v181 offset:32768
	ds_read_b128 v[218:221], v181 offset:33792
	ds_read_b128 v[222:225], v181 offset:34816
	ds_read_b128 v[226:229], v181 offset:35840
	ds_read_b128 v[230:233], v181 offset:36864
	ds_read_b128 v[234:237], v181 offset:37888
	ds_read_b128 v[238:241], v181 offset:38912
	ds_read_b128 v[242:245], v181 offset:39936
	global_load_lds_dwordx4 v[250:251], off
	v_lshl_add_u64 v[250:251], s[0:1], 0, v[164:165]
	s_mov_b32 m0, s43
	s_nop 0
	global_load_lds_dwordx4 v[250:251], off
	s_waitcnt vmcnt(8)
	s_waitcnt lgkmcnt(0)
	s_barrier
	s_setprio 1
	s_waitcnt lgkmcnt(0)
	v_mfma_f32_16x16x32_bf16 v[124:127], v[128:131], v[214:217], v[124:127]
	v_mfma_f32_16x16x32_bf16 v[120:123], v[136:139], v[214:217], v[120:123]
	v_mfma_f32_16x16x32_bf16 v[108:111], v[128:131], v[222:225], v[108:111]
	v_mfma_f32_16x16x32_bf16 v[104:107], v[136:139], v[222:225], v[104:107]
	v_mfma_f32_16x16x32_bf16 v[92:95], v[128:131], v[230:233], v[92:95]
	v_mfma_f32_16x16x32_bf16 v[88:91], v[136:139], v[230:233], v[88:91]
	v_mfma_f32_16x16x32_bf16 v[76:79], v[128:131], v[238:241], v[76:79]
	v_mfma_f32_16x16x32_bf16 v[72:75], v[136:139], v[238:241], v[72:75]
	v_mfma_f32_16x16x32_bf16 v[124:127], v[132:135], v[218:221], v[124:127]
	v_mfma_f32_16x16x32_bf16 v[120:123], v[140:143], v[218:221], v[120:123]
	v_mfma_f32_16x16x32_bf16 v[108:111], v[132:135], v[226:229], v[108:111]
	v_mfma_f32_16x16x32_bf16 v[104:107], v[140:143], v[226:229], v[104:107]
	v_mfma_f32_16x16x32_bf16 v[92:95], v[132:135], v[234:237], v[92:95]
	v_mfma_f32_16x16x32_bf16 v[88:91], v[140:143], v[234:237], v[88:91]
	v_mfma_f32_16x16x32_bf16 v[76:79], v[132:135], v[242:245], v[76:79]
	v_mfma_f32_16x16x32_bf16 v[72:75], v[140:143], v[242:245], v[72:75]
	s_setprio 0
	s_setprio 1
	v_mfma_f32_16x16x32_bf16 v[116:119], v[174:177], v[214:217], v[116:119]
	v_mfma_f32_16x16x32_bf16 v[112:115], v[188:191], v[214:217], v[112:115]
	v_mfma_f32_16x16x32_bf16 v[100:103], v[174:177], v[222:225], v[100:103]
	v_mfma_f32_16x16x32_bf16 v[96:99], v[188:191], v[222:225], v[96:99]
	v_mfma_f32_16x16x32_bf16 v[84:87], v[174:177], v[230:233], v[84:87]
	v_mfma_f32_16x16x32_bf16 v[80:83], v[188:191], v[230:233], v[80:83]
	v_mfma_f32_16x16x32_bf16 v[68:71], v[174:177], v[238:241], v[68:71]
	v_mfma_f32_16x16x32_bf16 v[64:67], v[188:191], v[238:241], v[64:67]
	v_mfma_f32_16x16x32_bf16 v[116:119], v[184:187], v[218:221], v[116:119]
	v_mfma_f32_16x16x32_bf16 v[112:115], v[210:213], v[218:221], v[112:115]
	v_mfma_f32_16x16x32_bf16 v[100:103], v[184:187], v[226:229], v[100:103]
	v_mfma_f32_16x16x32_bf16 v[96:99], v[210:213], v[226:229], v[96:99]
	v_mfma_f32_16x16x32_bf16 v[84:87], v[184:187], v[234:237], v[84:87]
	v_mfma_f32_16x16x32_bf16 v[80:83], v[210:213], v[234:237], v[80:83]
	v_mfma_f32_16x16x32_bf16 v[68:71], v[184:187], v[242:245], v[68:71]
	v_mfma_f32_16x16x32_bf16 v[64:67], v[210:213], v[242:245], v[64:67]
	s_setprio 0
	s_barrier
; #define PG8_STAGE(bufoff, gbase, voff) do { _Pragma("unroll") for (int _i = 0; _i < 2; ++_i) \
;         __builtin_amdgcn_global_load_lds((const unsigned*)((const char*)(gbase) + (voff)[_i]), (PG8_LAS unsigned*)(lds + (bufoff) + ldsw + _i * 8192), 16, 0, 0); } while (0)
; #define PG8_LDA(dst, b, h) do { _Pragma("unroll") for (int m = 0; m < 4; ++m) _Pragma("unroll") for (int k = 0; k < 2; ++k) dst[m][k] = *(const PG8_LAS bf16x8*)(lds + PG8_SA(b, h) + aoff + m * 2048 + k * 1024); } while (0)
; #define PG8_MMA(ai, bj, At, Bt) do { __builtin_amdgcn_s_setprio(1); _Pragma("unroll") for (int m = 0; m < 4; ++m) _Pragma("unroll") for (int n = 0; n < 2; ++n) _Pragma("unroll") for (int k = 0; k < 2; ++k) \
;         acc[ai][bj][m][n] = __builtin_amdgcn_mfma_f32_16x16x32_bf16(Bt[n][k], At[m][k], acc[ai][bj][m][n], 0, 0, 0); __builtin_amdgcn_s_setprio(0); } while (0)
; #define PG8_WAIT_V(n) asm volatile("s_waitcnt vmcnt(" #n ")" ::: "memory")
; #define PG8_WAIT_L(n) asm volatile("s_waitcnt lgkmcnt(" #n ")" ::: "memory")
; #define PG8_BAR __builtin_amdgcn_s_barrier()
; #define PG8_SCHED __builtin_amdgcn_sched_barrier(0)
; template <class Epi, class Sched, bool ALIGN_EPI = false, bool SP2 = false>
; __device__ __forceinline__ void gemm_phase(PG8_LAS unsigned char* lds, const Gemm g, const Sched& S, const Epi& E) {
;     ...
;         for (int t = 0; t < nt; t += 2) {
;             const bool last = (t == nt - 2);
;             const char* a1 = cA + (size_t)(t + 1) * kstep;
;             const char* a2 = last ? nA : cA + (size_t)(t + 2) * kstep; const char* b2 = last ? nB : cB + (size_t)(t + 2) * kstep;
;             const char* a3 = a2 + kstep; const char* b3 = b2 + kstep;
;     ...
;             PG8_LDA(At, 1, 1); PG8_STAGE(PG8_SB(1, 0), b3, voffB); PG8_STAGE(PG8_SB(1, 1), b3 + hstep, voffB); PG8_STAGE(PG8_SA(1, 0), a3, voffA);
;             PG8_WAIT_V(8); PG8_WAIT_L(0); PG8_BAR; PG8_MMA(1, 0, At, B0); PG8_MMA(1, 1, At, B1); PG8_BAR; PG8_SCHED;
	s_mov_b32 m0, s47
	v_lshl_add_u64 v[178:179], v[178:179], 0, s[94:95]
	s_add_u32 s0, s4, 0xb0080
	ds_read_b128 v[214:217], v181 offset:49152
	ds_read_b128 v[218:221], v181 offset:50176
	ds_read_b128 v[222:225], v181 offset:51200
	ds_read_b128 v[226:229], v181 offset:52224
	ds_read_b128 v[230:233], v181 offset:53248
	ds_read_b128 v[234:237], v181 offset:54272
	ds_read_b128 v[238:241], v181 offset:55296
	ds_read_b128 v[242:245], v181 offset:56320
	global_load_lds_dwordx4 v[178:179], off
	v_lshl_add_u64 v[178:179], v[208:209], 0, s[94:95]
	s_mov_b32 m0, s48
	s_addc_u32 s1, s5, 0
	global_load_lds_dwordx4 v[178:179], off
	v_lshl_add_u64 v[178:179], s[0:1], 0, v[166:167]
	s_mov_b32 m0, s51
	s_nop 0
	global_load_lds_dwordx4 v[178:179], off
	v_lshl_add_u64 v[178:179], s[0:1], 0, v[162:163]
	s_mov_b32 m0, s52
	s_nop 0
	global_load_lds_dwordx4 v[178:179], off
	v_lshl_add_u64 v[178:179], v[246:247], 0, s[94:95]
	s_mov_b32 m0, s49
	s_nop 0
	global_load_lds_dwordx4 v[178:179], off
	v_lshl_add_u64 v[178:179], v[248:249], 0, s[94:95]
	s_mov_b32 m0, s50
	s_nop 0
	global_load_lds_dwordx4 v[178:179], off
	s_waitcnt vmcnt(8)
	s_waitcnt lgkmcnt(0)
	s_barrier
	s_setprio 1
	s_waitcnt lgkmcnt(0)
	v_mfma_f32_16x16x32_bf16 v[60:63], v[128:131], v[214:217], v[60:63]
	v_mfma_f32_16x16x32_bf16 v[56:59], v[136:139], v[214:217], v[56:59]
	v_mfma_f32_16x16x32_bf16 v[44:47], v[128:131], v[222:225], v[44:47]
	v_mfma_f32_16x16x32_bf16 v[40:43], v[136:139], v[222:225], v[40:43]
	v_mfma_f32_16x16x32_bf16 v[28:31], v[128:131], v[230:233], v[28:31]
	v_mfma_f32_16x16x32_bf16 v[24:27], v[136:139], v[230:233], v[24:27]
	v_mfma_f32_16x16x32_bf16 v[12:15], v[128:131], v[238:241], v[12:15]
	v_mfma_f32_16x16x32_bf16 v[8:11], v[136:139], v[238:241], v[8:11]
	v_mfma_f32_16x16x32_bf16 v[60:63], v[132:135], v[218:221], v[60:63]
	v_mfma_f32_16x16x32_bf16 v[56:59], v[140:143], v[218:221], v[56:59]
	v_mfma_f32_16x16x32_bf16 v[44:47], v[132:135], v[226:229], v[44:47]
	v_mfma_f32_16x16x32_bf16 v[40:43], v[140:143], v[226:229], v[40:43]
	v_mfma_f32_16x16x32_bf16 v[28:31], v[132:135], v[234:237], v[28:31]
	v_mfma_f32_16x16x32_bf16 v[24:27], v[140:143], v[234:237], v[24:27]
	v_mfma_f32_16x16x32_bf16 v[12:15], v[132:135], v[242:245], v[12:15]
	v_mfma_f32_16x16x32_bf16 v[8:11], v[140:143], v[242:245], v[8:11]
	s_setprio 0
	s_setprio 1
	v_mfma_f32_16x16x32_bf16 v[52:55], v[174:177], v[214:217], v[52:55]
	v_mfma_f32_16x16x32_bf16 v[48:51], v[188:191], v[214:217], v[48:51]
	v_mfma_f32_16x16x32_bf16 v[36:39], v[174:177], v[222:225], v[36:39]
	v_mfma_f32_16x16x32_bf16 v[32:35], v[188:191], v[222:225], v[32:35]
	v_mfma_f32_16x16x32_bf16 v[20:23], v[174:177], v[230:233], v[20:23]
	v_mfma_f32_16x16x32_bf16 v[16:19], v[188:191], v[230:233], v[16:19]
	v_mfma_f32_16x16x32_bf16 v[4:7], v[174:177], v[238:241], v[4:7]
	v_mfma_f32_16x16x32_bf16 v[0:3], v[188:191], v[238:241], v[0:3]
	v_mfma_f32_16x16x32_bf16 v[52:55], v[184:187], v[218:221], v[52:55]
	v_mfma_f32_16x16x32_bf16 v[48:51], v[210:213], v[218:221], v[48:51]
	v_mfma_f32_16x16x32_bf16 v[36:39], v[184:187], v[226:229], v[36:39]
	v_mfma_f32_16x16x32_bf16 v[32:35], v[210:213], v[226:229], v[32:35]
	v_mfma_f32_16x16x32_bf16 v[20:23], v[184:187], v[234:237], v[20:23]
	v_mfma_f32_16x16x32_bf16 v[16:19], v[210:213], v[234:237], v[16:19]
	v_mfma_f32_16x16x32_bf16 v[4:7], v[184:187], v[242:245], v[4:7]
	v_mfma_f32_16x16x32_bf16 v[0:3], v[210:213], v[242:245], v[0:3]
	s_setprio 0
	s_barrier
	s_add_i32 s13, s13, 2
	s_add_u32 s10, s10, 0x100
	s_addc_u32 s11, s11, 0
	s_cmp_gt_u32 s13, 41
	s_mov_b64 s[0:1], s[2:3]

; #define PG8_STAGE(bufoff, gbase, voff) do { _Pragma("unroll") for (int _i = 0; _i < 2; ++_i) \
;         __builtin_amdgcn_global_load_lds((const unsigned*)((const char*)(gbase) + (voff)[_i]), (PG8_LAS unsigned*)(lds + (bufoff) + ldsw + _i * 8192), 16, 0, 0); } while (0)
; #define PG8_LDA(dst, b, h) do { _Pragma("unroll") for (int m = 0; m < 4; ++m) _Pragma("unroll") for (int k = 0; k < 2; ++k) dst[m][k] = *(const PG8_LAS bf16x8*)(lds + PG8_SA(b, h) + aoff + m * 2048 + k * 1024); } while (0)
; #define PG8_LDB(dst, b, h) do { _Pragma("unroll") for (int n = 0; n < 2; ++n) _Pragma("unroll") for (int k = 0; k < 2; ++k) dst[n][k] = *(const PG8_LAS bf16x8*)(lds + PG8_SB(b, h) + boff + n * 2048 + k * 1024); } while (0)
; #define PG8_MMA(ai, bj, At, Bt) do { __builtin_amdgcn_s_setprio(1); _Pragma("unroll") for (int m = 0; m < 4; ++m) _Pragma("unroll") for (int n = 0; n < 2; ++n) _Pragma("unroll") for (int k = 0; k < 2; ++k) \
;         acc[ai][bj][m][n] = __builtin_amdgcn_mfma_f32_16x16x32_bf16(Bt[n][k], At[m][k], acc[ai][bj][m][n], 0, 0, 0); __builtin_amdgcn_s_setprio(0); } while (0)
; #define PG8_BAR __builtin_amdgcn_s_barrier()
; template <class Epi, class Sched, bool ALIGN_EPI = false, bool SP2 = false>
; __device__ __forceinline__ void gemm_phase(PG8_LAS unsigned char* lds, const Gemm g, const Sched& S, const Epi& E) {
;     ...
;         const bool has_next = S.next(ui + 1, nxt);
;         const char* nA = has_next ? (const char*)g.A + (size_t)nxt.pm * tstep : cA; const char* nB = has_next ? (const char*)g.Bt + (size_t)nxt.pn * tstep : cB;
;         for (int t = 0; t < nt; t += 2) {
;             const bool last = (t == nt - 2);
;             const char* a1 = cA + (size_t)(t + 1) * kstep;
;             const char* a2 = last ? nA : cA + (size_t)(t + 2) * kstep; const char* b2 = last ? nB : cB + (size_t)(t + 2) * kstep;
;             const char* a3 = a2 + kstep; const char* b3 = b2 + kstep;
;             if (last && has_next) S.a_ready(nxt);
;             if constexpr (SP2) {
;             PG8_LDB(B0, 0, 0); PG8_LDB(B1, 0, 1); PG8_SCHED; PG8_LDA(At, 0, 0); PG8_STAGE(PG8_SA(1, 1), a1 + hstep, voffA);
;             PG8_WAIT_V(8); PG8_WAIT_L(0); PG8_BAR; PG8_MMA(0, 0, At, B0); PG8_MMA(0, 1, At, B1); PG8_BAR; PG8_SCHED;
;             PG8_LDA(At, 0, 1); PG8_STAGE(PG8_SB(0, 0), b2, voffB); PG8_STAGE(PG8_SB(0, 1), b2 + hstep, voffB); PG8_STAGE(PG8_SA(0, 0), a2, voffA);
.LBB0_748:
	s_ashr_i32 s25, s24, 31
	s_lshl_b64 s[4:5], s[24:25], 19
	s_add_u32 s26, s7, s4
	s_addc_u32 s27, s28, s5
	s_and_b64 s[4:5], s[8:9], exec
	s_cselect_b32 s13, s27, s1
	s_cselect_b32 s25, s26, s0
	s_ashr_i32 s23, s22, 31
	s_lshl_b64 s[4:5], s[22:23], 19
	s_add_u32 s36, s29, s4
	s_addc_u32 s37, s30, s5
	s_and_b64 s[4:5], s[8:9], exec
	s_cselect_b32 s23, s37, s3
	s_cselect_b32 s33, s36, s2
	s_add_u32 s0, s0, 0x40080
	s_addc_u32 s1, s1, 0
	s_add_u32 s38, s2, 0x100
	v_mov_b32_e32 v0, 0
	s_addc_u32 s39, s3, 0
	s_mov_b32 s55, -2
	s_waitcnt lgkmcnt(0)
.Lsgi_peel:
	v_or_b32_e32 v140, 0x10000, v179
	v_add_u32_e32 v147, 0x10400, v179
	ds_read_b128 v[140:143], v140
	ds_read_b128 v[162:165], v147
	v_add_u32_e32 v147, 0x10800, v179
	v_add_u32_e32 v170, 0x10c00, v179
	ds_read_b128 v[166:169], v147
	ds_read_b128 v[170:173], v170
	v_or_b32_e32 v147, 0x14000, v179
	v_add_u32_e32 v174, 0x14400, v179
	ds_read_b128 v[180:183], v147
	ds_read_b128 v[184:187], v174
	v_add_u32_e32 v147, 0x14800, v179
	v_add_u32_e32 v174, 0x14c00, v179
	ds_read_b128 v[188:191], v147
	ds_read_b128 v[210:213], v174
	s_add_u32 s2, s0, 0xfffc0080
	s_addc_u32 s3, s1, -1
	s_cmp_eq_u32 s55, 12
	s_cselect_b32 s5, s13, s3
	s_cselect_b32 s4, s25, s2
	s_cselect_b32 s3, s23, s39
	s_cselect_b32 s2, s33, s38
	v_lshl_add_u64 v[174:175], s[0:1], 0, v[136:137]
	s_add_i32 m0, s6, 0xc000
	ds_read_b128 v[214:217], v178
	ds_read_b128 v[218:221], v178 offset:1024
	ds_read_b128 v[222:225], v178 offset:2048
	ds_read_b128 v[226:229], v178 offset:3072
	ds_read_b128 v[230:233], v178 offset:4096
	ds_read_b128 v[234:237], v178 offset:5120
	ds_read_b128 v[238:241], v178 offset:6144
	ds_read_b128 v[242:245], v178 offset:7168
	global_load_lds_dwordx4 v[174:175], off
	v_lshl_add_u64 v[174:175], s[0:1], 0, v[138:139]
	s_add_i32 m0, s6, 0xe000
	s_nop 0
	global_load_lds_dwordx4 v[174:175], off
	s_waitcnt vmcnt(8)
	s_waitcnt lgkmcnt(0)
	s_barrier
	s_setprio 1
	s_waitcnt lgkmcnt(0)
	v_mfma_f32_16x16x32_bf16 v[124:127], v[140:143], v[214:217], 0
	v_mfma_f32_16x16x32_bf16 v[120:123], v[166:169], v[214:217], 0
	v_mfma_f32_16x16x32_bf16 v[108:111], v[140:143], v[222:225], 0
	v_mfma_f32_16x16x32_bf16 v[104:107], v[166:169], v[222:225], 0
	v_mfma_f32_16x16x32_bf16 v[92:95], v[140:143], v[230:233], 0
	v_mfma_f32_16x16x32_bf16 v[88:91], v[166:169], v[230:233], 0
	v_mfma_f32_16x16x32_bf16 v[76:79], v[140:143], v[238:241], 0
	v_mfma_f32_16x16x32_bf16 v[72:75], v[166:169], v[238:241], 0
	v_mfma_f32_16x16x32_bf16 v[124:127], v[162:165], v[218:221], v[124:127]
	v_mfma_f32_16x16x32_bf16 v[120:123], v[170:173], v[218:221], v[120:123]
	v_mfma_f32_16x16x32_bf16 v[108:111], v[162:165], v[226:229], v[108:111]
	v_mfma_f32_16x16x32_bf16 v[104:107], v[170:173], v[226:229], v[104:107]
	v_mfma_f32_16x16x32_bf16 v[92:95], v[162:165], v[234:237], v[92:95]
	v_mfma_f32_16x16x32_bf16 v[88:91], v[170:173], v[234:237], v[88:91]
	v_mfma_f32_16x16x32_bf16 v[76:79], v[162:165], v[242:245], v[76:79]
	v_mfma_f32_16x16x32_bf16 v[72:75], v[170:173], v[242:245], v[72:75]
	s_setprio 0
	s_setprio 1
	v_mfma_f32_16x16x32_bf16 v[116:119], v[180:183], v[214:217], 0
	v_mfma_f32_16x16x32_bf16 v[112:115], v[188:191], v[214:217], 0
	v_mfma_f32_16x16x32_bf16 v[100:103], v[180:183], v[222:225], 0
	v_mfma_f32_16x16x32_bf16 v[96:99], v[188:191], v[222:225], 0
	v_mfma_f32_16x16x32_bf16 v[84:87], v[180:183], v[230:233], 0
	v_mfma_f32_16x16x32_bf16 v[80:83], v[188:191], v[230:233], 0
	v_mfma_f32_16x16x32_bf16 v[68:71], v[180:183], v[238:241], 0
	v_mfma_f32_16x16x32_bf16 v[64:67], v[188:191], v[238:241], 0
	v_mfma_f32_16x16x32_bf16 v[116:119], v[184:187], v[218:221], v[116:119]
	v_mfma_f32_16x16x32_bf16 v[112:115], v[210:213], v[218:221], v[112:115]
	v_mfma_f32_16x16x32_bf16 v[100:103], v[184:187], v[226:229], v[100:103]
	v_mfma_f32_16x16x32_bf16 v[96:99], v[210:213], v[226:229], v[96:99]
	v_mfma_f32_16x16x32_bf16 v[84:87], v[184:187], v[234:237], v[84:87]
	v_mfma_f32_16x16x32_bf16 v[80:83], v[210:213], v[234:237], v[80:83]
	v_mfma_f32_16x16x32_bf16 v[68:71], v[184:187], v[242:245], v[68:71]
	v_mfma_f32_16x16x32_bf16 v[64:67], v[210:213], v[242:245], v[64:67]
	s_setprio 0
	s_barrier
	s_mov_b32 m0, s31
	v_lshl_add_u64 v[174:175], s[2:3], 0, v[132:133]
	s_add_u32 s56, s2, 0x40000
	ds_read_b128 v[214:217], v178 offset:16384
	ds_read_b128 v[218:221], v178 offset:17408
	ds_read_b128 v[222:225], v178 offset:18432
	ds_read_b128 v[226:229], v178 offset:19456
	ds_read_b128 v[230:233], v178 offset:20480
	ds_read_b128 v[234:237], v178 offset:21504
	ds_read_b128 v[238:241], v178 offset:22528
	ds_read_b128 v[242:245], v178 offset:23552
	global_load_lds_dwordx4 v[174:175], off
	v_lshl_add_u64 v[208:209], s[2:3], 0, v[128:129]
	s_mov_b32 m0, s34
	s_addc_u32 s57, s3, 0
	global_load_lds_dwordx4 v[208:209], off
	v_lshl_add_u64 v[246:247], s[56:57], 0, v[132:133]
	s_mov_b32 m0, s35
	v_lshl_add_u64 v[248:249], s[4:5], 0, v[130:131]
	global_load_lds_dwordx4 v[246:247], off
	v_lshl_add_u64 v[246:247], s[56:57], 0, v[128:129]
	s_mov_b32 m0, s40
	s_nop 0
	global_load_lds_dwordx4 v[246:247], off
	v_lshl_add_u64 v[246:247], s[4:5], 0, v[134:135]
	s_mov_b32 m0, s6
	s_nop 0
	global_load_lds_dwordx4 v[246:247], off
	s_mov_b32 m0, s41
	s_nop 0
	global_load_lds_dwordx4 v[248:249], off
	s_waitcnt vmcnt(8)
	s_waitcnt lgkmcnt(0)
	s_barrier
; #define PG8_STAGE(bufoff, gbase, voff) do { _Pragma("unroll") for (int _i = 0; _i < 2; ++_i) \
;         __builtin_amdgcn_global_load_lds((const unsigned*)((const char*)(gbase) + (voff)[_i]), (PG8_LAS unsigned*)(lds + (bufoff) + ldsw + _i * 8192), 16, 0, 0); } while (0)
; #define PG8_LDA(dst, b, h) do { _Pragma("unroll") for (int m = 0; m < 4; ++m) _Pragma("unroll") for (int k = 0; k < 2; ++k) dst[m][k] = *(const PG8_LAS bf16x8*)(lds + PG8_SA(b, h) + aoff + m * 2048 + k * 1024); } while (0)
; #define PG8_LDB(dst, b, h) do { _Pragma("unroll") for (int n = 0; n < 2; ++n) _Pragma("unroll") for (int k = 0; k < 2; ++k) dst[n][k] = *(const PG8_LAS bf16x8*)(lds + PG8_SB(b, h) + boff + n * 2048 + k * 1024); } while (0)
; #define PG8_MMA(ai, bj, At, Bt) do { __builtin_amdgcn_s_setprio(1); _Pragma("unroll") for (int m = 0; m < 4; ++m) _Pragma("unroll") for (int n = 0; n < 2; ++n) _Pragma("unroll") for (int k = 0; k < 2; ++k) \
;         acc[ai][bj][m][n] = __builtin_amdgcn_mfma_f32_16x16x32_bf16(Bt[n][k], At[m][k], acc[ai][bj][m][n], 0, 0, 0); __builtin_amdgcn_s_setprio(0); } while (0)
; #define PG8_WAIT_V(n) asm volatile("s_waitcnt vmcnt(" #n ")" ::: "memory")
; #define PG8_WAIT_L(n) asm volatile("s_waitcnt lgkmcnt(" #n ")" ::: "memory")
; #define PG8_BAR __builtin_amdgcn_s_barrier()
; #define PG8_SCHED __builtin_amdgcn_sched_barrier(0)
; template <class Epi, class Sched, bool ALIGN_EPI = false, bool SP2 = false>
; __device__ __forceinline__ void gemm_phase(PG8_LAS unsigned char* lds, const Gemm g, const Sched& S, const Epi& E) {
;     ...
;             PG8_WAIT_V(8); PG8_WAIT_L(0); PG8_BAR; PG8_MMA(1, 0, At, B0); PG8_MMA(1, 1, At, B1); PG8_BAR; PG8_SCHED;
;             PG8_LDB(B0, 1, 0); PG8_LDB(B1, 1, 1); PG8_SCHED; PG8_LDA(At, 1, 0); PG8_STAGE(PG8_SA(0, 1), a2 + hstep, voffA);
;             PG8_WAIT_V(8); PG8_WAIT_L(0); PG8_BAR; PG8_MMA(0, 0, At, B0); PG8_MMA(0, 1, At, B1); PG8_BAR; PG8_SCHED;
	s_setprio 1
	s_waitcnt lgkmcnt(0)
	v_mfma_f32_16x16x32_bf16 v[60:63], v[140:143], v[214:217], 0
	v_mfma_f32_16x16x32_bf16 v[56:59], v[166:169], v[214:217], 0
	v_mfma_f32_16x16x32_bf16 v[44:47], v[140:143], v[222:225], 0
	v_mfma_f32_16x16x32_bf16 v[40:43], v[166:169], v[222:225], 0
	v_mfma_f32_16x16x32_bf16 v[28:31], v[140:143], v[230:233], 0
	v_mfma_f32_16x16x32_bf16 v[24:27], v[166:169], v[230:233], 0
	v_mfma_f32_16x16x32_bf16 v[12:15], v[140:143], v[238:241], 0
	v_mfma_f32_16x16x32_bf16 v[8:11], v[166:169], v[238:241], 0
	v_mfma_f32_16x16x32_bf16 v[60:63], v[162:165], v[218:221], v[60:63]
	v_mfma_f32_16x16x32_bf16 v[56:59], v[170:173], v[218:221], v[56:59]
	v_mfma_f32_16x16x32_bf16 v[44:47], v[162:165], v[226:229], v[44:47]
	v_mfma_f32_16x16x32_bf16 v[40:43], v[170:173], v[226:229], v[40:43]
	v_mfma_f32_16x16x32_bf16 v[28:31], v[162:165], v[234:237], v[28:31]
	v_mfma_f32_16x16x32_bf16 v[24:27], v[170:173], v[234:237], v[24:27]
	v_mfma_f32_16x16x32_bf16 v[12:15], v[162:165], v[242:245], v[12:15]
	v_mfma_f32_16x16x32_bf16 v[8:11], v[170:173], v[242:245], v[8:11]
	s_setprio 0
	s_setprio 1
	v_mfma_f32_16x16x32_bf16 v[52:55], v[180:183], v[214:217], 0
	v_mfma_f32_16x16x32_bf16 v[48:51], v[188:191], v[214:217], 0
	v_mfma_f32_16x16x32_bf16 v[36:39], v[180:183], v[222:225], 0
	v_mfma_f32_16x16x32_bf16 v[32:35], v[188:191], v[222:225], 0
	v_mfma_f32_16x16x32_bf16 v[20:23], v[180:183], v[230:233], 0
	v_mfma_f32_16x16x32_bf16 v[16:19], v[188:191], v[230:233], 0
	v_mfma_f32_16x16x32_bf16 v[4:7], v[180:183], v[238:241], 0
	v_mfma_f32_16x16x32_bf16 v[0:3], v[188:191], v[238:241], 0
	v_mfma_f32_16x16x32_bf16 v[52:55], v[184:187], v[218:221], v[52:55]
	v_mfma_f32_16x16x32_bf16 v[48:51], v[210:213], v[218:221], v[48:51]
	v_mfma_f32_16x16x32_bf16 v[36:39], v[184:187], v[226:229], v[36:39]
	v_mfma_f32_16x16x32_bf16 v[32:35], v[210:213], v[226:229], v[32:35]
	v_mfma_f32_16x16x32_bf16 v[20:23], v[184:187], v[234:237], v[20:23]
	v_mfma_f32_16x16x32_bf16 v[16:19], v[210:213], v[234:237], v[16:19]
	v_mfma_f32_16x16x32_bf16 v[4:7], v[184:187], v[242:245], v[4:7]
	v_mfma_f32_16x16x32_bf16 v[0:3], v[210:213], v[242:245], v[0:3]
	s_setprio 0
	s_barrier
	v_or_b32_e32 v140, 0x18000, v179
	v_add_u32_e32 v147, 0x18400, v179
	ds_read_b128 v[140:143], v140
	ds_read_b128 v[162:165], v147
	v_add_u32_e32 v147, 0x18800, v179
	v_add_u32_e32 v170, 0x18c00, v179
	ds_read_b128 v[166:169], v147
	ds_read_b128 v[170:173], v170
	v_or_b32_e32 v147, 0x1c000, v179
	v_add_u32_e32 v184, 0x1c400, v179
	ds_read_b128 v[180:183], v147
	ds_read_b128 v[184:187], v184
	v_add_u32_e32 v147, 0x1c800, v179
	v_add_u32_e32 v210, 0x1cc00, v179
	ds_read_b128 v[188:191], v147
	ds_read_b128 v[210:213], v210
	s_add_u32 s4, s4, 0x40000
	s_addc_u32 s5, s5, 0
	s_mov_b32 m0, s42
	v_lshl_add_u64 v[250:251], s[4:5], 0, v[134:135]
	ds_read_b128 v[214:217], v178 offset:32768
	ds_read_b128 v[218:221], v178 offset:33792
	ds_read_b128 v[222:225], v178 offset:34816
	ds_read_b128 v[226:229], v178 offset:35840
	ds_read_b128 v[230:233], v178 offset:36864
	ds_read_b128 v[234:237], v178 offset:37888
	ds_read_b128 v[238:241], v178 offset:38912
	ds_read_b128 v[242:245], v178 offset:39936
	global_load_lds_dwordx4 v[250:251], off
	v_lshl_add_u64 v[250:251], s[4:5], 0, v[130:131]
	s_mov_b32 m0, s43
	s_nop 0
	global_load_lds_dwordx4 v[250:251], off
	s_waitcnt vmcnt(8)
	s_waitcnt lgkmcnt(0)
	s_barrier
	s_setprio 1
	s_waitcnt lgkmcnt(0)
	v_mfma_f32_16x16x32_bf16 v[124:127], v[140:143], v[214:217], v[124:127]
	v_mfma_f32_16x16x32_bf16 v[120:123], v[166:169], v[214:217], v[120:123]
	v_mfma_f32_16x16x32_bf16 v[108:111], v[140:143], v[222:225], v[108:111]
	v_mfma_f32_16x16x32_bf16 v[104:107], v[166:169], v[222:225], v[104:107]
	v_mfma_f32_16x16x32_bf16 v[92:95], v[140:143], v[230:233], v[92:95]
	v_mfma_f32_16x16x32_bf16 v[88:91], v[166:169], v[230:233], v[88:91]
	v_mfma_f32_16x16x32_bf16 v[76:79], v[140:143], v[238:241], v[76:79]
	v_mfma_f32_16x16x32_bf16 v[72:75], v[166:169], v[238:241], v[72:75]
	v_mfma_f32_16x16x32_bf16 v[124:127], v[162:165], v[218:221], v[124:127]
	v_mfma_f32_16x16x32_bf16 v[120:123], v[170:173], v[218:221], v[120:123]
	v_mfma_f32_16x16x32_bf16 v[108:111], v[162:165], v[226:229], v[108:111]
	v_mfma_f32_16x16x32_bf16 v[104:107], v[170:173], v[226:229], v[104:107]
	v_mfma_f32_16x16x32_bf16 v[92:95], v[162:165], v[234:237], v[92:95]
	v_mfma_f32_16x16x32_bf16 v[88:91], v[170:173], v[234:237], v[88:91]
	v_mfma_f32_16x16x32_bf16 v[76:79], v[162:165], v[242:245], v[76:79]
	v_mfma_f32_16x16x32_bf16 v[72:75], v[170:173], v[242:245], v[72:75]
	s_setprio 0
	s_setprio 1
	v_mfma_f32_16x16x32_bf16 v[116:119], v[180:183], v[214:217], v[116:119]
	v_mfma_f32_16x16x32_bf16 v[112:115], v[188:191], v[214:217], v[112:115]
	v_mfma_f32_16x16x32_bf16 v[100:103], v[180:183], v[222:225], v[100:103]
	v_mfma_f32_16x16x32_bf16 v[96:99], v[188:191], v[222:225], v[96:99]
	v_mfma_f32_16x16x32_bf16 v[84:87], v[180:183], v[230:233], v[84:87]
	v_mfma_f32_16x16x32_bf16 v[80:83], v[188:191], v[230:233], v[80:83]
	v_mfma_f32_16x16x32_bf16 v[68:71], v[180:183], v[238:241], v[68:71]
	v_mfma_f32_16x16x32_bf16 v[64:67], v[188:191], v[238:241], v[64:67]
	v_mfma_f32_16x16x32_bf16 v[116:119], v[184:187], v[218:221], v[116:119]
	v_mfma_f32_16x16x32_bf16 v[112:115], v[210:213], v[218:221], v[112:115]
	v_mfma_f32_16x16x32_bf16 v[100:103], v[184:187], v[226:229], v[100:103]
	v_mfma_f32_16x16x32_bf16 v[96:99], v[210:213], v[226:229], v[96:99]
	v_mfma_f32_16x16x32_bf16 v[84:87], v[184:187], v[234:237], v[84:87]
	v_mfma_f32_16x16x32_bf16 v[80:83], v[210:213], v[234:237], v[80:83]
	v_mfma_f32_16x16x32_bf16 v[68:71], v[184:187], v[242:245], v[68:71]
	v_mfma_f32_16x16x32_bf16 v[64:67], v[210:213], v[242:245], v[64:67]
	s_setprio 0
	s_barrier
; #define PG8_STAGE(bufoff, gbase, voff) do { _Pragma("unroll") for (int _i = 0; _i < 2; ++_i) \
;         __builtin_amdgcn_global_load_lds((const unsigned*)((const char*)(gbase) + (voff)[_i]), (PG8_LAS unsigned*)(lds + (bufoff) + ldsw + _i * 8192), 16, 0, 0); } while (0)
; #define PG8_LDA(dst, b, h) do { _Pragma("unroll") for (int m = 0; m < 4; ++m) _Pragma("unroll") for (int k = 0; k < 2; ++k) dst[m][k] = *(const PG8_LAS bf16x8*)(lds + PG8_SA(b, h) + aoff + m * 2048 + k * 1024); } while (0)
; #define PG8_MMA(ai, bj, At, Bt) do { __builtin_amdgcn_s_setprio(1); _Pragma("unroll") for (int m = 0; m < 4; ++m) _Pragma("unroll") for (int n = 0; n < 2; ++n) _Pragma("unroll") for (int k = 0; k < 2; ++k) \
;         acc[ai][bj][m][n] = __builtin_amdgcn_mfma_f32_16x16x32_bf16(Bt[n][k], At[m][k], acc[ai][bj][m][n], 0, 0, 0); __builtin_amdgcn_s_setprio(0); } while (0)
; #define PG8_WAIT_V(n) asm volatile("s_waitcnt vmcnt(" #n ")" ::: "memory")
; #define PG8_WAIT_L(n) asm volatile("s_waitcnt lgkmcnt(" #n ")" ::: "memory")
; #define PG8_BAR __builtin_amdgcn_s_barrier()
; #define PG8_SCHED __builtin_amdgcn_sched_barrier(0)
; template <class Epi, class Sched, bool ALIGN_EPI = false, bool SP2 = false>
; __device__ __forceinline__ void gemm_phase(PG8_LAS unsigned char* lds, const Gemm g, const Sched& S, const Epi& E) {
;     ...
;         for (int t = 0; t < nt; t += 2) {
;             const bool last = (t == nt - 2);
;             const char* a1 = cA + (size_t)(t + 1) * kstep;
;             const char* a2 = last ? nA : cA + (size_t)(t + 2) * kstep; const char* b2 = last ? nB : cB + (size_t)(t + 2) * kstep;
;             const char* a3 = a2 + kstep; const char* b3 = b2 + kstep;
;     ...
;             PG8_LDA(At, 1, 1); PG8_STAGE(PG8_SB(1, 0), b3, voffB); PG8_STAGE(PG8_SB(1, 1), b3 + hstep, voffB); PG8_STAGE(PG8_SA(1, 0), a3, voffA);
;             PG8_WAIT_V(8); PG8_WAIT_L(0); PG8_BAR; PG8_MMA(1, 0, At, B0); PG8_MMA(1, 1, At, B1); PG8_BAR; PG8_SCHED;
	s_mov_b32 m0, s48
	v_lshl_add_u64 v[174:175], v[174:175], 0, s[94:95]
	s_add_u32 s2, s2, 0x40080
	ds_read_b128 v[214:217], v178 offset:49152
	ds_read_b128 v[218:221], v178 offset:50176
	ds_read_b128 v[222:225], v178 offset:51200
	ds_read_b128 v[226:229], v178 offset:52224
	ds_read_b128 v[230:233], v178 offset:53248
	ds_read_b128 v[234:237], v178 offset:54272
	ds_read_b128 v[238:241], v178 offset:55296
	ds_read_b128 v[242:245], v178 offset:56320
	global_load_lds_dwordx4 v[174:175], off
	v_lshl_add_u64 v[174:175], v[208:209], 0, s[94:95]
	s_mov_b32 m0, s49
	s_addc_u32 s3, s3, 0
	global_load_lds_dwordx4 v[174:175], off
	v_lshl_add_u64 v[174:175], s[2:3], 0, v[132:133]
	s_mov_b32 m0, s52
	s_nop 0
	global_load_lds_dwordx4 v[174:175], off
	v_lshl_add_u64 v[174:175], s[2:3], 0, v[128:129]
	s_mov_b32 m0, s53
	s_nop 0
	global_load_lds_dwordx4 v[174:175], off
	v_lshl_add_u64 v[174:175], v[246:247], 0, s[94:95]
	s_mov_b32 m0, s50
	s_nop 0
	global_load_lds_dwordx4 v[174:175], off
	v_lshl_add_u64 v[174:175], v[248:249], 0, s[94:95]
	s_mov_b32 m0, s51
	s_nop 0
	global_load_lds_dwordx4 v[174:175], off
	s_waitcnt vmcnt(8)
	s_waitcnt lgkmcnt(0)
	s_barrier
	s_setprio 1
	s_waitcnt lgkmcnt(0)
	v_mfma_f32_16x16x32_bf16 v[60:63], v[140:143], v[214:217], v[60:63]
	v_mfma_f32_16x16x32_bf16 v[56:59], v[166:169], v[214:217], v[56:59]
	v_mfma_f32_16x16x32_bf16 v[44:47], v[140:143], v[222:225], v[44:47]
	v_mfma_f32_16x16x32_bf16 v[40:43], v[166:169], v[222:225], v[40:43]
	v_mfma_f32_16x16x32_bf16 v[28:31], v[140:143], v[230:233], v[28:31]
	v_mfma_f32_16x16x32_bf16 v[24:27], v[166:169], v[230:233], v[24:27]
	v_mfma_f32_16x16x32_bf16 v[12:15], v[140:143], v[238:241], v[12:15]
	v_mfma_f32_16x16x32_bf16 v[8:11], v[166:169], v[238:241], v[8:11]
	v_mfma_f32_16x16x32_bf16 v[60:63], v[162:165], v[218:221], v[60:63]
	v_mfma_f32_16x16x32_bf16 v[56:59], v[170:173], v[218:221], v[56:59]
	v_mfma_f32_16x16x32_bf16 v[44:47], v[162:165], v[226:229], v[44:47]
	v_mfma_f32_16x16x32_bf16 v[40:43], v[170:173], v[226:229], v[40:43]
	v_mfma_f32_16x16x32_bf16 v[28:31], v[162:165], v[234:237], v[28:31]
	v_mfma_f32_16x16x32_bf16 v[24:27], v[170:173], v[234:237], v[24:27]
	v_mfma_f32_16x16x32_bf16 v[12:15], v[162:165], v[242:245], v[12:15]
	v_mfma_f32_16x16x32_bf16 v[8:11], v[170:173], v[242:245], v[8:11]
	s_setprio 0
	s_setprio 1
	v_mfma_f32_16x16x32_bf16 v[52:55], v[180:183], v[214:217], v[52:55]
	v_mfma_f32_16x16x32_bf16 v[48:51], v[188:191], v[214:217], v[48:51]
	v_mfma_f32_16x16x32_bf16 v[36:39], v[180:183], v[222:225], v[36:39]
	v_mfma_f32_16x16x32_bf16 v[32:35], v[188:191], v[222:225], v[32:35]
	v_mfma_f32_16x16x32_bf16 v[20:23], v[180:183], v[230:233], v[20:23]
	v_mfma_f32_16x16x32_bf16 v[16:19], v[188:191], v[230:233], v[16:19]
	v_mfma_f32_16x16x32_bf16 v[4:7], v[180:183], v[238:241], v[4:7]
	v_mfma_f32_16x16x32_bf16 v[0:3], v[188:191], v[238:241], v[0:3]
	v_mfma_f32_16x16x32_bf16 v[52:55], v[184:187], v[218:221], v[52:55]
	v_mfma_f32_16x16x32_bf16 v[48:51], v[210:213], v[218:221], v[48:51]
	v_mfma_f32_16x16x32_bf16 v[36:39], v[184:187], v[226:229], v[36:39]
	v_mfma_f32_16x16x32_bf16 v[32:35], v[210:213], v[226:229], v[32:35]
	v_mfma_f32_16x16x32_bf16 v[20:23], v[184:187], v[234:237], v[20:23]
	v_mfma_f32_16x16x32_bf16 v[16:19], v[210:213], v[234:237], v[16:19]
	v_mfma_f32_16x16x32_bf16 v[4:7], v[184:187], v[242:245], v[4:7]
	v_mfma_f32_16x16x32_bf16 v[0:3], v[210:213], v[242:245], v[0:3]
	s_setprio 0
	s_barrier
	s_add_i32 s55, s55, 2
	s_add_u32 s0, s0, 0x100
	s_addc_u32 s1, s1, 0
	s_add_u32 s38, s38, 0x100
	s_addc_u32 s39, s39, 0
	s_cmp_gt_u32 s55, 13

; #define PG8_STAGE(bufoff, gbase, voff) do { _Pragma("unroll") for (int _i = 0; _i < 2; ++_i) \
;         __builtin_amdgcn_global_load_lds((const unsigned*)((const char*)(gbase) + (voff)[_i]), (PG8_LAS unsigned*)(lds + (bufoff) + ldsw + _i * 8192), 16, 0, 0); } while (0)
; #define PG8_LDA(dst, b, h) do { _Pragma("unroll") for (int m = 0; m < 4; ++m) _Pragma("unroll") for (int k = 0; k < 2; ++k) dst[m][k] = *(const PG8_LAS bf16x8*)(lds + PG8_SA(b, h) + aoff + m * 2048 + k * 1024); } while (0)
; #define PG8_LDB(dst, b, h) do { _Pragma("unroll") for (int n = 0; n < 2; ++n) _Pragma("unroll") for (int k = 0; k < 2; ++k) dst[n][k] = *(const PG8_LAS bf16x8*)(lds + PG8_SB(b, h) + boff + n * 2048 + k * 1024); } while (0)
; #define PG8_MMA(ai, bj, At, Bt) do { __builtin_amdgcn_s_setprio(1); _Pragma("unroll") for (int m = 0; m < 4; ++m) _Pragma("unroll") for (int n = 0; n < 2; ++n) _Pragma("unroll") for (int k = 0; k < 2; ++k) \
;         acc[ai][bj][m][n] = __builtin_amdgcn_mfma_f32_16x16x32_bf16(Bt[n][k], At[m][k], acc[ai][bj][m][n], 0, 0, 0); __builtin_amdgcn_s_setprio(0); } while (0)
; #define PG8_WAIT_V(n) asm volatile("s_waitcnt vmcnt(" #n ")" ::: "memory")
; #define PG8_WAIT_L(n) asm volatile("s_waitcnt lgkmcnt(" #n ")" ::: "memory")
; #define PG8_BAR __builtin_amdgcn_s_barrier()
; #define PG8_SCHED __builtin_amdgcn_sched_barrier(0)
; template <class Epi, class Sched, bool ALIGN_EPI = false, bool SP2 = false>
; __device__ __forceinline__ void gemm_phase(PG8_LAS unsigned char* lds, const Gemm g, const Sched& S, const Epi& E) {
;     ...
;             PG8_LDB(B0, 0, 0); PG8_LDB(B1, 0, 1); PG8_SCHED; PG8_LDA(At, 0, 0); PG8_STAGE(PG8_SA(1, 1), a1 + hstep, voffA);
;             PG8_WAIT_V(8); PG8_WAIT_L(0); PG8_BAR; PG8_MMA(0, 0, At, B0); PG8_MMA(0, 1, At, B1); PG8_BAR; PG8_SCHED;
;             PG8_LDA(At, 0, 1); PG8_STAGE(PG8_SB(0, 0), b2, voffB); PG8_STAGE(PG8_SB(0, 1), b2 + hstep, voffB); PG8_STAGE(PG8_SA(0, 0), a2, voffA);
.Labi_peel:
	s_waitcnt lgkmcnt(0)
	v_or_b32_e32 v140, 0x10000, v174
	v_add_u32_e32 v162, 0x10400, v174
	v_add_u32_e32 v166, 0x10800, v174
	v_add_u32_e32 v170, 0x10c00, v174
	ds_read_b128 v[140:143], v140
	ds_read_b128 v[162:165], v162
	ds_read_b128 v[166:169], v166
	ds_read_b128 v[176:179], v170
	v_or_b32_e32 v170, 0x14000, v174
	v_add_u32_e32 v171, 0x14400, v174
	ds_read_b128 v[180:183], v170
	ds_read_b128 v[184:187], v171
	v_add_u32_e32 v170, 0x14800, v174
	v_add_u32_e32 v171, 0x14c00, v174
	ds_read_b128 v[188:191], v170
	ds_read_b128 v[210:213], v171
	s_add_u32 s2, s0, 0xfffc0080
	s_addc_u32 s3, s1, -1
	s_cmp_eq_u32 s52, 12
	s_cselect_b32 s5, s17, s3
	s_cselect_b32 s4, s48, s2
	s_cselect_b32 s3, s15, s51
	s_cselect_b32 s2, s49, s50
	v_lshl_add_u64 v[170:171], s[0:1], 0, v[136:137]
	s_add_i32 m0, s6, 0xc000
	ds_read_b128 v[214:217], v173
	ds_read_b128 v[218:221], v173 offset:1024
	ds_read_b128 v[222:225], v173 offset:2048
	ds_read_b128 v[226:229], v173 offset:3072
	ds_read_b128 v[230:233], v173 offset:4096
	ds_read_b128 v[234:237], v173 offset:5120
	ds_read_b128 v[238:241], v173 offset:6144
	ds_read_b128 v[242:245], v173 offset:7168
	global_load_lds_dwordx4 v[170:171], off
	v_lshl_add_u64 v[170:171], s[0:1], 0, v[138:139]
	s_add_i32 m0, s6, 0xe000
	s_nop 0
	global_load_lds_dwordx4 v[170:171], off
	s_waitcnt vmcnt(8)
	s_waitcnt lgkmcnt(0)
	s_barrier
	s_setprio 1
	s_waitcnt lgkmcnt(0)
	v_mfma_f32_16x16x32_bf16 v[124:127], v[140:143], v[214:217], 0
	v_mfma_f32_16x16x32_bf16 v[120:123], v[166:169], v[214:217], 0
	v_mfma_f32_16x16x32_bf16 v[112:115], v[140:143], v[222:225], 0
	v_mfma_f32_16x16x32_bf16 v[104:107], v[166:169], v[222:225], 0
	v_mfma_f32_16x16x32_bf16 v[96:99], v[140:143], v[230:233], 0
	v_mfma_f32_16x16x32_bf16 v[88:91], v[166:169], v[230:233], 0
	v_mfma_f32_16x16x32_bf16 v[80:83], v[140:143], v[238:241], 0
	v_mfma_f32_16x16x32_bf16 v[72:75], v[166:169], v[238:241], 0
	v_mfma_f32_16x16x32_bf16 v[124:127], v[162:165], v[218:221], v[124:127]
	v_mfma_f32_16x16x32_bf16 v[120:123], v[176:179], v[218:221], v[120:123]
	v_mfma_f32_16x16x32_bf16 v[112:115], v[162:165], v[226:229], v[112:115]
	v_mfma_f32_16x16x32_bf16 v[104:107], v[176:179], v[226:229], v[104:107]
	v_mfma_f32_16x16x32_bf16 v[96:99], v[162:165], v[234:237], v[96:99]
	v_mfma_f32_16x16x32_bf16 v[88:91], v[176:179], v[234:237], v[88:91]
	v_mfma_f32_16x16x32_bf16 v[80:83], v[162:165], v[242:245], v[80:83]
	v_mfma_f32_16x16x32_bf16 v[72:75], v[176:179], v[242:245], v[72:75]
	s_setprio 0
	s_setprio 1
	v_mfma_f32_16x16x32_bf16 v[116:119], v[180:183], v[214:217], 0
	v_mfma_f32_16x16x32_bf16 v[108:111], v[188:191], v[214:217], 0
	v_mfma_f32_16x16x32_bf16 v[100:103], v[180:183], v[222:225], 0
	v_mfma_f32_16x16x32_bf16 v[92:95], v[188:191], v[222:225], 0
	v_mfma_f32_16x16x32_bf16 v[84:87], v[180:183], v[230:233], 0
	v_mfma_f32_16x16x32_bf16 v[76:79], v[188:191], v[230:233], 0
	v_mfma_f32_16x16x32_bf16 v[68:71], v[180:183], v[238:241], 0
	v_mfma_f32_16x16x32_bf16 v[64:67], v[188:191], v[238:241], 0
	v_mfma_f32_16x16x32_bf16 v[116:119], v[184:187], v[218:221], v[116:119]
	v_mfma_f32_16x16x32_bf16 v[108:111], v[210:213], v[218:221], v[108:111]
	v_mfma_f32_16x16x32_bf16 v[100:103], v[184:187], v[226:229], v[100:103]
	v_mfma_f32_16x16x32_bf16 v[92:95], v[210:213], v[226:229], v[92:95]
	v_mfma_f32_16x16x32_bf16 v[84:87], v[184:187], v[234:237], v[84:87]
	v_mfma_f32_16x16x32_bf16 v[76:79], v[210:213], v[234:237], v[76:79]
	v_mfma_f32_16x16x32_bf16 v[68:71], v[184:187], v[242:245], v[68:71]
	v_mfma_f32_16x16x32_bf16 v[64:67], v[210:213], v[242:245], v[64:67]
	s_setprio 0
	s_barrier
	s_mov_b32 m0, s27
	v_lshl_add_u64 v[170:171], s[2:3], 0, v[132:133]
	s_add_u32 s54, s2, 0x40000
	ds_read_b128 v[214:217], v173 offset:16384
	ds_read_b128 v[218:221], v173 offset:17408
	ds_read_b128 v[222:225], v173 offset:18432
	ds_read_b128 v[226:229], v173 offset:19456
	ds_read_b128 v[230:233], v173 offset:20480
	ds_read_b128 v[234:237], v173 offset:21504
	ds_read_b128 v[238:241], v173 offset:22528
	ds_read_b128 v[242:245], v173 offset:23552
	global_load_lds_dwordx4 v[170:171], off
	v_lshl_add_u64 v[208:209], s[2:3], 0, v[128:129]
	s_mov_b32 m0, s28
	s_addc_u32 s55, s3, 0
	global_load_lds_dwordx4 v[208:209], off
	v_lshl_add_u64 v[246:247], s[54:55], 0, v[132:133]
	s_mov_b32 m0, s29
	v_lshl_add_u64 v[248:249], s[4:5], 0, v[130:131]
	global_load_lds_dwordx4 v[246:247], off
	v_lshl_add_u64 v[246:247], s[54:55], 0, v[128:129]
	s_mov_b32 m0, s30
	s_nop 0
	global_load_lds_dwordx4 v[246:247], off
	v_lshl_add_u64 v[246:247], s[4:5], 0, v[134:135]
	s_mov_b32 m0, s6
	s_nop 0
	global_load_lds_dwordx4 v[246:247], off
	s_mov_b32 m0, s31
	s_nop 0
	global_load_lds_dwordx4 v[248:249], off
	s_waitcnt vmcnt(8)
	s_waitcnt lgkmcnt(0)
	s_barrier
; #define PG8_STAGE(bufoff, gbase, voff) do { _Pragma("unroll") for (int _i = 0; _i < 2; ++_i) \
;         __builtin_amdgcn_global_load_lds((const unsigned*)((const char*)(gbase) + (voff)[_i]), (PG8_LAS unsigned*)(lds + (bufoff) + ldsw + _i * 8192), 16, 0, 0); } while (0)
; #define PG8_LDA(dst, b, h) do { _Pragma("unroll") for (int m = 0; m < 4; ++m) _Pragma("unroll") for (int k = 0; k < 2; ++k) dst[m][k] = *(const PG8_LAS bf16x8*)(lds + PG8_SA(b, h) + aoff + m * 2048 + k * 1024); } while (0)
; #define PG8_LDB(dst, b, h) do { _Pragma("unroll") for (int n = 0; n < 2; ++n) _Pragma("unroll") for (int k = 0; k < 2; ++k) dst[n][k] = *(const PG8_LAS bf16x8*)(lds + PG8_SB(b, h) + boff + n * 2048 + k * 1024); } while (0)
; #define PG8_MMA(ai, bj, At, Bt) do { __builtin_amdgcn_s_setprio(1); _Pragma("unroll") for (int m = 0; m < 4; ++m) _Pragma("unroll") for (int n = 0; n < 2; ++n) _Pragma("unroll") for (int k = 0; k < 2; ++k) \
;         acc[ai][bj][m][n] = __builtin_amdgcn_mfma_f32_16x16x32_bf16(Bt[n][k], At[m][k], acc[ai][bj][m][n], 0, 0, 0); __builtin_amdgcn_s_setprio(0); } while (0)
; #define PG8_WAIT_V(n) asm volatile("s_waitcnt vmcnt(" #n ")" ::: "memory")
; #define PG8_WAIT_L(n) asm volatile("s_waitcnt lgkmcnt(" #n ")" ::: "memory")
; #define PG8_BAR __builtin_amdgcn_s_barrier()
; #define PG8_SCHED __builtin_amdgcn_sched_barrier(0)
; template <class Epi, class Sched, bool ALIGN_EPI = false, bool SP2 = false>
; __device__ __forceinline__ void gemm_phase(PG8_LAS unsigned char* lds, const Gemm g, const Sched& S, const Epi& E) {
;     ...
;             PG8_WAIT_V(8); PG8_WAIT_L(0); PG8_BAR; PG8_MMA(1, 0, At, B0); PG8_MMA(1, 1, At, B1); PG8_BAR; PG8_SCHED;
;             PG8_LDB(B0, 1, 0); PG8_LDB(B1, 1, 1); PG8_SCHED; PG8_LDA(At, 1, 0); PG8_STAGE(PG8_SA(0, 1), a2 + hstep, voffA);
;             PG8_WAIT_V(8); PG8_WAIT_L(0); PG8_BAR; PG8_MMA(0, 0, At, B0); PG8_MMA(0, 1, At, B1); PG8_BAR; PG8_SCHED;
	s_setprio 1
	s_waitcnt lgkmcnt(0)
	v_mfma_f32_16x16x32_bf16 v[60:63], v[140:143], v[214:217], 0
	v_mfma_f32_16x16x32_bf16 v[56:59], v[166:169], v[214:217], 0
	v_mfma_f32_16x16x32_bf16 v[48:51], v[140:143], v[222:225], 0
	v_mfma_f32_16x16x32_bf16 v[40:43], v[166:169], v[222:225], 0
	v_mfma_f32_16x16x32_bf16 v[32:35], v[140:143], v[230:233], 0
	v_mfma_f32_16x16x32_bf16 v[24:27], v[166:169], v[230:233], 0
	v_mfma_f32_16x16x32_bf16 v[16:19], v[140:143], v[238:241], 0
	v_mfma_f32_16x16x32_bf16 v[8:11], v[166:169], v[238:241], 0
	v_mfma_f32_16x16x32_bf16 v[60:63], v[162:165], v[218:221], v[60:63]
	v_mfma_f32_16x16x32_bf16 v[56:59], v[176:179], v[218:221], v[56:59]
	v_mfma_f32_16x16x32_bf16 v[48:51], v[162:165], v[226:229], v[48:51]
	v_mfma_f32_16x16x32_bf16 v[40:43], v[176:179], v[226:229], v[40:43]
	v_mfma_f32_16x16x32_bf16 v[32:35], v[162:165], v[234:237], v[32:35]
	v_mfma_f32_16x16x32_bf16 v[24:27], v[176:179], v[234:237], v[24:27]
	v_mfma_f32_16x16x32_bf16 v[16:19], v[162:165], v[242:245], v[16:19]
	v_mfma_f32_16x16x32_bf16 v[8:11], v[176:179], v[242:245], v[8:11]
	s_setprio 0
	s_setprio 1
	v_mfma_f32_16x16x32_bf16 v[52:55], v[180:183], v[214:217], 0
	v_mfma_f32_16x16x32_bf16 v[44:47], v[188:191], v[214:217], 0
	v_mfma_f32_16x16x32_bf16 v[36:39], v[180:183], v[222:225], 0
	v_mfma_f32_16x16x32_bf16 v[28:31], v[188:191], v[222:225], 0
	v_mfma_f32_16x16x32_bf16 v[20:23], v[180:183], v[230:233], 0
	v_mfma_f32_16x16x32_bf16 v[12:15], v[188:191], v[230:233], 0
	v_mfma_f32_16x16x32_bf16 v[4:7], v[180:183], v[238:241], 0
	v_mfma_f32_16x16x32_bf16 v[0:3], v[188:191], v[238:241], 0
	v_mfma_f32_16x16x32_bf16 v[52:55], v[184:187], v[218:221], v[52:55]
	v_mfma_f32_16x16x32_bf16 v[44:47], v[210:213], v[218:221], v[44:47]
	v_mfma_f32_16x16x32_bf16 v[36:39], v[184:187], v[226:229], v[36:39]
	v_mfma_f32_16x16x32_bf16 v[28:31], v[210:213], v[226:229], v[28:31]
	v_mfma_f32_16x16x32_bf16 v[20:23], v[184:187], v[234:237], v[20:23]
	v_mfma_f32_16x16x32_bf16 v[12:15], v[210:213], v[234:237], v[12:15]
	v_mfma_f32_16x16x32_bf16 v[4:7], v[184:187], v[242:245], v[4:7]
	v_mfma_f32_16x16x32_bf16 v[0:3], v[210:213], v[242:245], v[0:3]
	s_setprio 0
	s_barrier
	v_or_b32_e32 v140, 0x18000, v174
	v_add_u32_e32 v162, 0x18400, v174
	v_add_u32_e32 v166, 0x18800, v174
	v_add_u32_e32 v175, 0x18c00, v174
	ds_read_b128 v[140:143], v140
	ds_read_b128 v[162:165], v162
	ds_read_b128 v[166:169], v166
	ds_read_b128 v[176:179], v175
	v_or_b32_e32 v175, 0x1c000, v174
	v_add_u32_e32 v184, 0x1c400, v174
	ds_read_b128 v[180:183], v175
	ds_read_b128 v[184:187], v184
	v_add_u32_e32 v175, 0x1c800, v174
	v_add_u32_e32 v210, 0x1cc00, v174
	ds_read_b128 v[188:191], v175
	ds_read_b128 v[210:213], v210
	s_add_u32 s4, s4, 0x40000
	s_addc_u32 s5, s5, 0
	s_mov_b32 m0, s33
	v_lshl_add_u64 v[250:251], s[4:5], 0, v[134:135]
	ds_read_b128 v[214:217], v173 offset:32768
	ds_read_b128 v[218:221], v173 offset:33792
	ds_read_b128 v[222:225], v173 offset:34816
	ds_read_b128 v[226:229], v173 offset:35840
	ds_read_b128 v[230:233], v173 offset:36864
	ds_read_b128 v[234:237], v173 offset:37888
	ds_read_b128 v[238:241], v173 offset:38912
	ds_read_b128 v[242:245], v173 offset:39936
	global_load_lds_dwordx4 v[250:251], off
	v_lshl_add_u64 v[250:251], s[4:5], 0, v[130:131]
	s_mov_b32 m0, s34
	s_nop 0
	global_load_lds_dwordx4 v[250:251], off
	s_waitcnt vmcnt(8)
	s_waitcnt lgkmcnt(0)
	s_barrier
	s_setprio 1
	s_waitcnt lgkmcnt(0)
	v_mfma_f32_16x16x32_bf16 v[124:127], v[140:143], v[214:217], v[124:127]
	v_mfma_f32_16x16x32_bf16 v[120:123], v[166:169], v[214:217], v[120:123]
	v_mfma_f32_16x16x32_bf16 v[112:115], v[140:143], v[222:225], v[112:115]
	v_mfma_f32_16x16x32_bf16 v[104:107], v[166:169], v[222:225], v[104:107]
	v_mfma_f32_16x16x32_bf16 v[96:99], v[140:143], v[230:233], v[96:99]
	v_mfma_f32_16x16x32_bf16 v[88:91], v[166:169], v[230:233], v[88:91]
	v_mfma_f32_16x16x32_bf16 v[80:83], v[140:143], v[238:241], v[80:83]
	v_mfma_f32_16x16x32_bf16 v[72:75], v[166:169], v[238:241], v[72:75]
	v_mfma_f32_16x16x32_bf16 v[124:127], v[162:165], v[218:221], v[124:127]
	v_mfma_f32_16x16x32_bf16 v[120:123], v[176:179], v[218:221], v[120:123]
	v_mfma_f32_16x16x32_bf16 v[112:115], v[162:165], v[226:229], v[112:115]
	v_mfma_f32_16x16x32_bf16 v[104:107], v[176:179], v[226:229], v[104:107]
	v_mfma_f32_16x16x32_bf16 v[96:99], v[162:165], v[234:237], v[96:99]
	v_mfma_f32_16x16x32_bf16 v[88:91], v[176:179], v[234:237], v[88:91]
	v_mfma_f32_16x16x32_bf16 v[80:83], v[162:165], v[242:245], v[80:83]
	v_mfma_f32_16x16x32_bf16 v[72:75], v[176:179], v[242:245], v[72:75]
	s_setprio 0
	s_setprio 1
	v_mfma_f32_16x16x32_bf16 v[116:119], v[180:183], v[214:217], v[116:119]
	v_mfma_f32_16x16x32_bf16 v[108:111], v[188:191], v[214:217], v[108:111]
	v_mfma_f32_16x16x32_bf16 v[100:103], v[180:183], v[222:225], v[100:103]
	v_mfma_f32_16x16x32_bf16 v[92:95], v[188:191], v[222:225], v[92:95]
	v_mfma_f32_16x16x32_bf16 v[84:87], v[180:183], v[230:233], v[84:87]
	v_mfma_f32_16x16x32_bf16 v[76:79], v[188:191], v[230:233], v[76:79]
	v_mfma_f32_16x16x32_bf16 v[68:71], v[180:183], v[238:241], v[68:71]
	v_mfma_f32_16x16x32_bf16 v[64:67], v[188:191], v[238:241], v[64:67]
	v_mfma_f32_16x16x32_bf16 v[116:119], v[184:187], v[218:221], v[116:119]
	v_mfma_f32_16x16x32_bf16 v[108:111], v[210:213], v[218:221], v[108:111]
	v_mfma_f32_16x16x32_bf16 v[100:103], v[184:187], v[226:229], v[100:103]
	v_mfma_f32_16x16x32_bf16 v[92:95], v[210:213], v[226:229], v[92:95]
	v_mfma_f32_16x16x32_bf16 v[84:87], v[184:187], v[234:237], v[84:87]
	v_mfma_f32_16x16x32_bf16 v[76:79], v[210:213], v[234:237], v[76:79]
	v_mfma_f32_16x16x32_bf16 v[68:71], v[184:187], v[242:245], v[68:71]
	v_mfma_f32_16x16x32_bf16 v[64:67], v[210:213], v[242:245], v[64:67]
	s_setprio 0
	s_barrier
; #define PG8_STAGE(bufoff, gbase, voff) do { _Pragma("unroll") for (int _i = 0; _i < 2; ++_i) \
;         __builtin_amdgcn_global_load_lds((const unsigned*)((const char*)(gbase) + (voff)[_i]), (PG8_LAS unsigned*)(lds + (bufoff) + ldsw + _i * 8192), 16, 0, 0); } while (0)
; #define PG8_LDA(dst, b, h) do { _Pragma("unroll") for (int m = 0; m < 4; ++m) _Pragma("unroll") for (int k = 0; k < 2; ++k) dst[m][k] = *(const PG8_LAS bf16x8*)(lds + PG8_SA(b, h) + aoff + m * 2048 + k * 1024); } while (0)
; #define PG8_MMA(ai, bj, At, Bt) do { __builtin_amdgcn_s_setprio(1); _Pragma("unroll") for (int m = 0; m < 4; ++m) _Pragma("unroll") for (int n = 0; n < 2; ++n) _Pragma("unroll") for (int k = 0; k < 2; ++k) \
;         acc[ai][bj][m][n] = __builtin_amdgcn_mfma_f32_16x16x32_bf16(Bt[n][k], At[m][k], acc[ai][bj][m][n], 0, 0, 0); __builtin_amdgcn_s_setprio(0); } while (0)
; #define PG8_WAIT_V(n) asm volatile("s_waitcnt vmcnt(" #n ")" ::: "memory")
; #define PG8_WAIT_L(n) asm volatile("s_waitcnt lgkmcnt(" #n ")" ::: "memory")
; #define PG8_BAR __builtin_amdgcn_s_barrier()
; #define PG8_SCHED __builtin_amdgcn_sched_barrier(0)
; template <class Epi, class Sched, bool ALIGN_EPI = false, bool SP2 = false>
; __device__ __forceinline__ void gemm_phase(PG8_LAS unsigned char* lds, const Gemm g, const Sched& S, const Epi& E) {
;     ...
;         for (int t = 0; t < nt; t += 2) {
;             const bool last = (t == nt - 2);
;             const char* a1 = cA + (size_t)(t + 1) * kstep;
;             const char* a2 = last ? nA : cA + (size_t)(t + 2) * kstep; const char* b2 = last ? nB : cB + (size_t)(t + 2) * kstep;
;             const char* a3 = a2 + kstep; const char* b3 = b2 + kstep;
;     ...
;             PG8_LDA(At, 1, 1); PG8_STAGE(PG8_SB(1, 0), b3, voffB); PG8_STAGE(PG8_SB(1, 1), b3 + hstep, voffB); PG8_STAGE(PG8_SA(1, 0), a3, voffA);
;             PG8_WAIT_V(8); PG8_WAIT_L(0); PG8_BAR; PG8_MMA(1, 0, At, B0); PG8_MMA(1, 1, At, B1); PG8_BAR; PG8_SCHED;
	s_mov_b32 m0, s37
	v_lshl_add_u64 v[170:171], v[170:171], 0, s[94:95]
	s_add_u32 s2, s2, 0x40080
	ds_read_b128 v[214:217], v173 offset:49152
	ds_read_b128 v[218:221], v173 offset:50176
	ds_read_b128 v[222:225], v173 offset:51200
	ds_read_b128 v[226:229], v173 offset:52224
	ds_read_b128 v[230:233], v173 offset:53248
	ds_read_b128 v[234:237], v173 offset:54272
	ds_read_b128 v[238:241], v173 offset:55296
	ds_read_b128 v[242:245], v173 offset:56320
	global_load_lds_dwordx4 v[170:171], off
	v_lshl_add_u64 v[170:171], v[208:209], 0, s[94:95]
	s_mov_b32 m0, s38
	s_addc_u32 s3, s3, 0
	global_load_lds_dwordx4 v[170:171], off
	v_lshl_add_u64 v[170:171], s[2:3], 0, v[132:133]
	s_mov_b32 m0, s41
	s_nop 0
	global_load_lds_dwordx4 v[170:171], off
	v_lshl_add_u64 v[170:171], s[2:3], 0, v[128:129]
	s_mov_b32 m0, s42
	s_nop 0
	global_load_lds_dwordx4 v[170:171], off
	v_lshl_add_u64 v[170:171], v[246:247], 0, s[94:95]
	s_mov_b32 m0, s39
	s_nop 0
	global_load_lds_dwordx4 v[170:171], off
	v_lshl_add_u64 v[170:171], v[248:249], 0, s[94:95]
	s_mov_b32 m0, s40
	s_nop 0
	global_load_lds_dwordx4 v[170:171], off
	s_waitcnt vmcnt(8)
	s_waitcnt lgkmcnt(0)
	s_barrier
	s_setprio 1
	s_waitcnt lgkmcnt(0)
	v_mfma_f32_16x16x32_bf16 v[60:63], v[140:143], v[214:217], v[60:63]
	v_mfma_f32_16x16x32_bf16 v[56:59], v[166:169], v[214:217], v[56:59]
	v_mfma_f32_16x16x32_bf16 v[48:51], v[140:143], v[222:225], v[48:51]
	v_mfma_f32_16x16x32_bf16 v[40:43], v[166:169], v[222:225], v[40:43]
	v_mfma_f32_16x16x32_bf16 v[32:35], v[140:143], v[230:233], v[32:35]
	v_mfma_f32_16x16x32_bf16 v[24:27], v[166:169], v[230:233], v[24:27]
	v_mfma_f32_16x16x32_bf16 v[16:19], v[140:143], v[238:241], v[16:19]
	v_mfma_f32_16x16x32_bf16 v[8:11], v[166:169], v[238:241], v[8:11]
	v_mfma_f32_16x16x32_bf16 v[60:63], v[162:165], v[218:221], v[60:63]
	v_mfma_f32_16x16x32_bf16 v[56:59], v[176:179], v[218:221], v[56:59]
	v_mfma_f32_16x16x32_bf16 v[48:51], v[162:165], v[226:229], v[48:51]
	v_mfma_f32_16x16x32_bf16 v[40:43], v[176:179], v[226:229], v[40:43]
	v_mfma_f32_16x16x32_bf16 v[32:35], v[162:165], v[234:237], v[32:35]
	v_mfma_f32_16x16x32_bf16 v[24:27], v[176:179], v[234:237], v[24:27]
	v_mfma_f32_16x16x32_bf16 v[16:19], v[162:165], v[242:245], v[16:19]
	v_mfma_f32_16x16x32_bf16 v[8:11], v[176:179], v[242:245], v[8:11]
	s_setprio 0
	s_setprio 1
	v_mfma_f32_16x16x32_bf16 v[52:55], v[180:183], v[214:217], v[52:55]
	v_mfma_f32_16x16x32_bf16 v[44:47], v[188:191], v[214:217], v[44:47]
	v_mfma_f32_16x16x32_bf16 v[36:39], v[180:183], v[222:225], v[36:39]
	v_mfma_f32_16x16x32_bf16 v[28:31], v[188:191], v[222:225], v[28:31]
	v_mfma_f32_16x16x32_bf16 v[20:23], v[180:183], v[230:233], v[20:23]
	v_mfma_f32_16x16x32_bf16 v[12:15], v[188:191], v[230:233], v[12:15]
	v_mfma_f32_16x16x32_bf16 v[4:7], v[180:183], v[238:241], v[4:7]
	v_mfma_f32_16x16x32_bf16 v[0:3], v[188:191], v[238:241], v[0:3]
	v_mfma_f32_16x16x32_bf16 v[52:55], v[184:187], v[218:221], v[52:55]
	v_mfma_f32_16x16x32_bf16 v[44:47], v[210:213], v[218:221], v[44:47]
	v_mfma_f32_16x16x32_bf16 v[36:39], v[184:187], v[226:229], v[36:39]
	v_mfma_f32_16x16x32_bf16 v[28:31], v[210:213], v[226:229], v[28:31]
	v_mfma_f32_16x16x32_bf16 v[20:23], v[184:187], v[234:237], v[20:23]
	v_mfma_f32_16x16x32_bf16 v[12:15], v[210:213], v[234:237], v[12:15]
	v_mfma_f32_16x16x32_bf16 v[4:7], v[184:187], v[242:245], v[4:7]
	v_mfma_f32_16x16x32_bf16 v[0:3], v[210:213], v[242:245], v[0:3]
	s_setprio 0
	s_barrier
	s_add_i32 s52, s52, 2
	s_add_u32 s0, s0, 0x100
	s_addc_u32 s1, s1, 0
	s_add_u32 s50, s50, 0x100
	s_addc_u32 s51, s51, 0
	s_cmp_gt_u32 s52, 13

; #define PG8_STAGE(bufoff, gbase, voff) do { _Pragma("unroll") for (int _i = 0; _i < 2; ++_i) \
;         __builtin_amdgcn_global_load_lds((const unsigned*)((const char*)(gbase) + (voff)[_i]), (PG8_LAS unsigned*)(lds + (bufoff) + ldsw + _i * 8192), 16, 0, 0); } while (0)
; #define PG8_LDA(dst, b, h) do { _Pragma("unroll") for (int m = 0; m < 4; ++m) _Pragma("unroll") for (int k = 0; k < 2; ++k) dst[m][k] = *(const PG8_LAS bf16x8*)(lds + PG8_SA(b, h) + aoff + m * 2048 + k * 1024); } while (0)
; #define PG8_LDB(dst, b, h) do { _Pragma("unroll") for (int n = 0; n < 2; ++n) _Pragma("unroll") for (int k = 0; k < 2; ++k) dst[n][k] = *(const PG8_LAS bf16x8*)(lds + PG8_SB(b, h) + boff + n * 2048 + k * 1024); } while (0)
; #define PG8_MMA(ai, bj, At, Bt) do { __builtin_amdgcn_s_setprio(1); _Pragma("unroll") for (int m = 0; m < 4; ++m) _Pragma("unroll") for (int n = 0; n < 2; ++n) _Pragma("unroll") for (int k = 0; k < 2; ++k) \
;         acc[ai][bj][m][n] = __builtin_amdgcn_mfma_f32_16x16x32_bf16(Bt[n][k], At[m][k], acc[ai][bj][m][n], 0, 0, 0); __builtin_amdgcn_s_setprio(0); } while (0)
; #define PG8_WAIT_V(n) asm volatile("s_waitcnt vmcnt(" #n ")" ::: "memory")
; #define PG8_WAIT_L(n) asm volatile("s_waitcnt lgkmcnt(" #n ")" ::: "memory")
; #define PG8_BAR __builtin_amdgcn_s_barrier()
; #define PG8_SCHED __builtin_amdgcn_sched_barrier(0)
; template <class Epi, class Sched, bool ALIGN_EPI = false, bool SP2 = false>
; __device__ __forceinline__ void gemm_phase(PG8_LAS unsigned char* lds, const Gemm g, const Sched& S, const Epi& E) {
;     ...
;             PG8_LDB(B0, 0, 0); PG8_LDB(B1, 0, 1); PG8_SCHED; PG8_LDA(At, 0, 0); PG8_STAGE(PG8_SA(1, 1), a1 + hstep, voffA);
;             PG8_WAIT_V(8); PG8_WAIT_L(0); PG8_BAR; PG8_MMA(0, 0, At, B0); PG8_MMA(0, 1, At, B1); PG8_BAR; PG8_SCHED;
;             PG8_LDA(At, 0, 1); PG8_STAGE(PG8_SB(0, 0), b2, voffB); PG8_STAGE(PG8_SB(0, 1), b2 + hstep, voffB); PG8_STAGE(PG8_SA(0, 0), a2, voffA);
.Lsgo_peel:
	v_or_b32_e32 v140, 0x10000, v164
	v_add_u32_e32 v165, 0x10400, v164
	ds_read_b128 v[140:143], v140
	ds_read_b128 v[166:169], v165
	v_add_u32_e32 v165, 0x10800, v164
	v_add_u32_e32 v174, 0x10c00, v164
	ds_read_b128 v[170:173], v165
	ds_read_b128 v[174:177], v174
	v_or_b32_e32 v165, 0x14000, v164
	v_add_u32_e32 v182, 0x14400, v164
	ds_read_b128 v[178:181], v165
	ds_read_b128 v[182:185], v182
	v_add_u32_e32 v165, 0x14800, v164
	v_add_u32_e32 v190, 0x14c00, v164
	ds_read_b128 v[186:189], v165
	ds_read_b128 v[210:213], v190
	s_add_u32 s2, s0, 0xfffc0080
	s_addc_u32 s3, s1, -1
	s_cmp_eq_u32 s55, 12
	s_cselect_b32 s5, s23, s3
	s_cselect_b32 s4, s51, s2
	s_cselect_b32 s3, s21, s54
	s_cselect_b32 s2, s52, s53
	v_lshl_add_u64 v[190:191], s[0:1], 0, v[136:137]
	s_add_i32 m0, s31, 0xc000
	ds_read_b128 v[214:217], v163
	ds_read_b128 v[218:221], v163 offset:1024
	ds_read_b128 v[222:225], v163 offset:2048
	ds_read_b128 v[226:229], v163 offset:3072
	ds_read_b128 v[230:233], v163 offset:4096
	ds_read_b128 v[234:237], v163 offset:5120
	ds_read_b128 v[238:241], v163 offset:6144
	ds_read_b128 v[242:245], v163 offset:7168
	global_load_lds_dwordx4 v[190:191], off
	v_lshl_add_u64 v[190:191], s[0:1], 0, v[138:139]
	s_add_i32 m0, s31, 0xe000
	s_nop 0
	global_load_lds_dwordx4 v[190:191], off
	s_waitcnt vmcnt(8)
	s_waitcnt lgkmcnt(0)
	s_barrier
	s_setprio 1
	s_waitcnt lgkmcnt(0)
	v_mfma_f32_16x16x32_bf16 v[124:127], v[140:143], v[214:217], 0
	v_mfma_f32_16x16x32_bf16 v[120:123], v[170:173], v[214:217], 0
	v_mfma_f32_16x16x32_bf16 v[108:111], v[140:143], v[222:225], 0
	v_mfma_f32_16x16x32_bf16 v[104:107], v[170:173], v[222:225], 0
	v_mfma_f32_16x16x32_bf16 v[92:95], v[140:143], v[230:233], 0
	v_mfma_f32_16x16x32_bf16 v[88:91], v[170:173], v[230:233], 0
	v_mfma_f32_16x16x32_bf16 v[76:79], v[140:143], v[238:241], 0
	v_mfma_f32_16x16x32_bf16 v[72:75], v[170:173], v[238:241], 0
	v_mfma_f32_16x16x32_bf16 v[124:127], v[166:169], v[218:221], v[124:127]
	v_mfma_f32_16x16x32_bf16 v[120:123], v[174:177], v[218:221], v[120:123]
	v_mfma_f32_16x16x32_bf16 v[108:111], v[166:169], v[226:229], v[108:111]
	v_mfma_f32_16x16x32_bf16 v[104:107], v[174:177], v[226:229], v[104:107]
	v_mfma_f32_16x16x32_bf16 v[92:95], v[166:169], v[234:237], v[92:95]
	v_mfma_f32_16x16x32_bf16 v[88:91], v[174:177], v[234:237], v[88:91]
	v_mfma_f32_16x16x32_bf16 v[76:79], v[166:169], v[242:245], v[76:79]
	v_mfma_f32_16x16x32_bf16 v[72:75], v[174:177], v[242:245], v[72:75]
	s_setprio 0
	s_setprio 1
	v_mfma_f32_16x16x32_bf16 v[116:119], v[178:181], v[214:217], 0
	v_mfma_f32_16x16x32_bf16 v[112:115], v[186:189], v[214:217], 0
	v_mfma_f32_16x16x32_bf16 v[100:103], v[178:181], v[222:225], 0
	v_mfma_f32_16x16x32_bf16 v[96:99], v[186:189], v[222:225], 0
	v_mfma_f32_16x16x32_bf16 v[84:87], v[178:181], v[230:233], 0
	v_mfma_f32_16x16x32_bf16 v[80:83], v[186:189], v[230:233], 0
	v_mfma_f32_16x16x32_bf16 v[68:71], v[178:181], v[238:241], 0
	v_mfma_f32_16x16x32_bf16 v[64:67], v[186:189], v[238:241], 0
	v_mfma_f32_16x16x32_bf16 v[116:119], v[182:185], v[218:221], v[116:119]
	v_mfma_f32_16x16x32_bf16 v[112:115], v[210:213], v[218:221], v[112:115]
	v_mfma_f32_16x16x32_bf16 v[100:103], v[182:185], v[226:229], v[100:103]
	v_mfma_f32_16x16x32_bf16 v[96:99], v[210:213], v[226:229], v[96:99]
	v_mfma_f32_16x16x32_bf16 v[84:87], v[182:185], v[234:237], v[84:87]
	v_mfma_f32_16x16x32_bf16 v[80:83], v[210:213], v[234:237], v[80:83]
	v_mfma_f32_16x16x32_bf16 v[68:71], v[182:185], v[242:245], v[68:71]
	v_mfma_f32_16x16x32_bf16 v[64:67], v[210:213], v[242:245], v[64:67]
	s_setprio 0
	s_barrier
	s_mov_b32 m0, s33
	v_lshl_add_u64 v[190:191], s[2:3], 0, v[132:133]
	s_add_u32 s56, s2, 0x40000
	ds_read_b128 v[214:217], v163 offset:16384
	ds_read_b128 v[218:221], v163 offset:17408
	ds_read_b128 v[222:225], v163 offset:18432
	ds_read_b128 v[226:229], v163 offset:19456
	ds_read_b128 v[230:233], v163 offset:20480
	ds_read_b128 v[234:237], v163 offset:21504
	ds_read_b128 v[238:241], v163 offset:22528
	ds_read_b128 v[242:245], v163 offset:23552
	global_load_lds_dwordx4 v[190:191], off
	v_lshl_add_u64 v[208:209], s[2:3], 0, v[128:129]
	s_mov_b32 m0, s34
	s_addc_u32 s57, s3, 0
	global_load_lds_dwordx4 v[208:209], off
	v_lshl_add_u64 v[246:247], s[56:57], 0, v[132:133]
	s_mov_b32 m0, s35
	v_lshl_add_u64 v[248:249], s[4:5], 0, v[130:131]
	global_load_lds_dwordx4 v[246:247], off
	v_lshl_add_u64 v[246:247], s[56:57], 0, v[128:129]
	s_mov_b32 m0, s36
	s_nop 0
	global_load_lds_dwordx4 v[246:247], off
	v_lshl_add_u64 v[246:247], s[4:5], 0, v[134:135]
	s_mov_b32 m0, s31
	s_nop 0
	global_load_lds_dwordx4 v[246:247], off
	s_mov_b32 m0, s37
	s_nop 0
	global_load_lds_dwordx4 v[248:249], off
	s_waitcnt vmcnt(8)
	s_waitcnt lgkmcnt(0)
	s_barrier
; #define PG8_STAGE(bufoff, gbase, voff) do { _Pragma("unroll") for (int _i = 0; _i < 2; ++_i) \
;         __builtin_amdgcn_global_load_lds((const unsigned*)((const char*)(gbase) + (voff)[_i]), (PG8_LAS unsigned*)(lds + (bufoff) + ldsw + _i * 8192), 16, 0, 0); } while (0)
; #define PG8_LDA(dst, b, h) do { _Pragma("unroll") for (int m = 0; m < 4; ++m) _Pragma("unroll") for (int k = 0; k < 2; ++k) dst[m][k] = *(const PG8_LAS bf16x8*)(lds + PG8_SA(b, h) + aoff + m * 2048 + k * 1024); } while (0)
; #define PG8_LDB(dst, b, h) do { _Pragma("unroll") for (int n = 0; n < 2; ++n) _Pragma("unroll") for (int k = 0; k < 2; ++k) dst[n][k] = *(const PG8_LAS bf16x8*)(lds + PG8_SB(b, h) + boff + n * 2048 + k * 1024); } while (0)
; #define PG8_MMA(ai, bj, At, Bt) do { __builtin_amdgcn_s_setprio(1); _Pragma("unroll") for (int m = 0; m < 4; ++m) _Pragma("unroll") for (int n = 0; n < 2; ++n) _Pragma("unroll") for (int k = 0; k < 2; ++k) \
;         acc[ai][bj][m][n] = __builtin_amdgcn_mfma_f32_16x16x32_bf16(Bt[n][k], At[m][k], acc[ai][bj][m][n], 0, 0, 0); __builtin_amdgcn_s_setprio(0); } while (0)
; #define PG8_WAIT_V(n) asm volatile("s_waitcnt vmcnt(" #n ")" ::: "memory")
; #define PG8_WAIT_L(n) asm volatile("s_waitcnt lgkmcnt(" #n ")" ::: "memory")
; #define PG8_BAR __builtin_amdgcn_s_barrier()
; #define PG8_SCHED __builtin_amdgcn_sched_barrier(0)
; template <class Epi, class Sched, bool ALIGN_EPI = false, bool SP2 = false>
; __device__ __forceinline__ void gemm_phase(PG8_LAS unsigned char* lds, const Gemm g, const Sched& S, const Epi& E) {
;     ...
;             PG8_WAIT_V(8); PG8_WAIT_L(0); PG8_BAR; PG8_MMA(1, 0, At, B0); PG8_MMA(1, 1, At, B1); PG8_BAR; PG8_SCHED;
;             PG8_LDB(B0, 1, 0); PG8_LDB(B1, 1, 1); PG8_SCHED; PG8_LDA(At, 1, 0); PG8_STAGE(PG8_SA(0, 1), a2 + hstep, voffA);
;             PG8_WAIT_V(8); PG8_WAIT_L(0); PG8_BAR; PG8_MMA(0, 0, At, B0); PG8_MMA(0, 1, At, B1); PG8_BAR; PG8_SCHED;
	s_setprio 1
	s_waitcnt lgkmcnt(0)
	v_mfma_f32_16x16x32_bf16 v[60:63], v[140:143], v[214:217], 0
	v_mfma_f32_16x16x32_bf16 v[56:59], v[170:173], v[214:217], 0
	v_mfma_f32_16x16x32_bf16 v[44:47], v[140:143], v[222:225], 0
	v_mfma_f32_16x16x32_bf16 v[40:43], v[170:173], v[222:225], 0
	v_mfma_f32_16x16x32_bf16 v[28:31], v[140:143], v[230:233], 0
	v_mfma_f32_16x16x32_bf16 v[24:27], v[170:173], v[230:233], 0
	v_mfma_f32_16x16x32_bf16 v[12:15], v[140:143], v[238:241], 0
	v_mfma_f32_16x16x32_bf16 v[8:11], v[170:173], v[238:241], 0
	v_mfma_f32_16x16x32_bf16 v[60:63], v[166:169], v[218:221], v[60:63]
	v_mfma_f32_16x16x32_bf16 v[56:59], v[174:177], v[218:221], v[56:59]
	v_mfma_f32_16x16x32_bf16 v[44:47], v[166:169], v[226:229], v[44:47]
	v_mfma_f32_16x16x32_bf16 v[40:43], v[174:177], v[226:229], v[40:43]
	v_mfma_f32_16x16x32_bf16 v[28:31], v[166:169], v[234:237], v[28:31]
	v_mfma_f32_16x16x32_bf16 v[24:27], v[174:177], v[234:237], v[24:27]
	v_mfma_f32_16x16x32_bf16 v[12:15], v[166:169], v[242:245], v[12:15]
	v_mfma_f32_16x16x32_bf16 v[8:11], v[174:177], v[242:245], v[8:11]
	s_setprio 0
	s_setprio 1
	v_mfma_f32_16x16x32_bf16 v[52:55], v[178:181], v[214:217], 0
	v_mfma_f32_16x16x32_bf16 v[48:51], v[186:189], v[214:217], 0
	v_mfma_f32_16x16x32_bf16 v[36:39], v[178:181], v[222:225], 0
	v_mfma_f32_16x16x32_bf16 v[32:35], v[186:189], v[222:225], 0
	v_mfma_f32_16x16x32_bf16 v[20:23], v[178:181], v[230:233], 0
	v_mfma_f32_16x16x32_bf16 v[16:19], v[186:189], v[230:233], 0
	v_mfma_f32_16x16x32_bf16 v[4:7], v[178:181], v[238:241], 0
	v_mfma_f32_16x16x32_bf16 v[0:3], v[186:189], v[238:241], 0
	v_mfma_f32_16x16x32_bf16 v[52:55], v[182:185], v[218:221], v[52:55]
	v_mfma_f32_16x16x32_bf16 v[48:51], v[210:213], v[218:221], v[48:51]
	v_mfma_f32_16x16x32_bf16 v[36:39], v[182:185], v[226:229], v[36:39]
	v_mfma_f32_16x16x32_bf16 v[32:35], v[210:213], v[226:229], v[32:35]
	v_mfma_f32_16x16x32_bf16 v[20:23], v[182:185], v[234:237], v[20:23]
	v_mfma_f32_16x16x32_bf16 v[16:19], v[210:213], v[234:237], v[16:19]
	v_mfma_f32_16x16x32_bf16 v[4:7], v[182:185], v[242:245], v[4:7]
	v_mfma_f32_16x16x32_bf16 v[0:3], v[210:213], v[242:245], v[0:3]
	s_setprio 0
	s_barrier
	v_or_b32_e32 v140, 0x18000, v164
	v_add_u32_e32 v165, 0x18400, v164
	ds_read_b128 v[140:143], v140
	ds_read_b128 v[166:169], v165
	v_add_u32_e32 v165, 0x18800, v164
	v_add_u32_e32 v174, 0x18c00, v164
	ds_read_b128 v[170:173], v165
	ds_read_b128 v[174:177], v174
	v_or_b32_e32 v165, 0x1c000, v164
	v_add_u32_e32 v182, 0x1c400, v164
	ds_read_b128 v[178:181], v165
	ds_read_b128 v[182:185], v182
	v_add_u32_e32 v165, 0x1c800, v164
	v_add_u32_e32 v210, 0x1cc00, v164
	ds_read_b128 v[186:189], v165
	ds_read_b128 v[210:213], v210
	s_add_u32 s4, s4, 0x40000
	s_addc_u32 s5, s5, 0
	s_mov_b32 m0, s38
	v_lshl_add_u64 v[250:251], s[4:5], 0, v[134:135]
	ds_read_b128 v[214:217], v163 offset:32768
	ds_read_b128 v[218:221], v163 offset:33792
	ds_read_b128 v[222:225], v163 offset:34816
	ds_read_b128 v[226:229], v163 offset:35840
	ds_read_b128 v[230:233], v163 offset:36864
	ds_read_b128 v[234:237], v163 offset:37888
	ds_read_b128 v[238:241], v163 offset:38912
	ds_read_b128 v[242:245], v163 offset:39936
	global_load_lds_dwordx4 v[250:251], off
	v_lshl_add_u64 v[250:251], s[4:5], 0, v[130:131]
	s_mov_b32 m0, s39
	s_nop 0
	global_load_lds_dwordx4 v[250:251], off
	s_waitcnt vmcnt(8)
	s_waitcnt lgkmcnt(0)
	s_barrier
	s_setprio 1
	s_waitcnt lgkmcnt(0)
	v_mfma_f32_16x16x32_bf16 v[124:127], v[140:143], v[214:217], v[124:127]
	v_mfma_f32_16x16x32_bf16 v[120:123], v[170:173], v[214:217], v[120:123]
	v_mfma_f32_16x16x32_bf16 v[108:111], v[140:143], v[222:225], v[108:111]
	v_mfma_f32_16x16x32_bf16 v[104:107], v[170:173], v[222:225], v[104:107]
	v_mfma_f32_16x16x32_bf16 v[92:95], v[140:143], v[230:233], v[92:95]
	v_mfma_f32_16x16x32_bf16 v[88:91], v[170:173], v[230:233], v[88:91]
	v_mfma_f32_16x16x32_bf16 v[76:79], v[140:143], v[238:241], v[76:79]
	v_mfma_f32_16x16x32_bf16 v[72:75], v[170:173], v[238:241], v[72:75]
	v_mfma_f32_16x16x32_bf16 v[124:127], v[166:169], v[218:221], v[124:127]
	v_mfma_f32_16x16x32_bf16 v[120:123], v[174:177], v[218:221], v[120:123]
	v_mfma_f32_16x16x32_bf16 v[108:111], v[166:169], v[226:229], v[108:111]
	v_mfma_f32_16x16x32_bf16 v[104:107], v[174:177], v[226:229], v[104:107]
	v_mfma_f32_16x16x32_bf16 v[92:95], v[166:169], v[234:237], v[92:95]
	v_mfma_f32_16x16x32_bf16 v[88:91], v[174:177], v[234:237], v[88:91]
	v_mfma_f32_16x16x32_bf16 v[76:79], v[166:169], v[242:245], v[76:79]
	v_mfma_f32_16x16x32_bf16 v[72:75], v[174:177], v[242:245], v[72:75]
	s_setprio 0
	s_setprio 1
	v_mfma_f32_16x16x32_bf16 v[116:119], v[178:181], v[214:217], v[116:119]
	v_mfma_f32_16x16x32_bf16 v[112:115], v[186:189], v[214:217], v[112:115]
	v_mfma_f32_16x16x32_bf16 v[100:103], v[178:181], v[222:225], v[100:103]
	v_mfma_f32_16x16x32_bf16 v[96:99], v[186:189], v[222:225], v[96:99]
	v_mfma_f32_16x16x32_bf16 v[84:87], v[178:181], v[230:233], v[84:87]
	v_mfma_f32_16x16x32_bf16 v[80:83], v[186:189], v[230:233], v[80:83]
	v_mfma_f32_16x16x32_bf16 v[68:71], v[178:181], v[238:241], v[68:71]
	v_mfma_f32_16x16x32_bf16 v[64:67], v[186:189], v[238:241], v[64:67]
	v_mfma_f32_16x16x32_bf16 v[116:119], v[182:185], v[218:221], v[116:119]
	v_mfma_f32_16x16x32_bf16 v[112:115], v[210:213], v[218:221], v[112:115]
	v_mfma_f32_16x16x32_bf16 v[100:103], v[182:185], v[226:229], v[100:103]
	v_mfma_f32_16x16x32_bf16 v[96:99], v[210:213], v[226:229], v[96:99]
	v_mfma_f32_16x16x32_bf16 v[84:87], v[182:185], v[234:237], v[84:87]
	v_mfma_f32_16x16x32_bf16 v[80:83], v[210:213], v[234:237], v[80:83]
	v_mfma_f32_16x16x32_bf16 v[68:71], v[182:185], v[242:245], v[68:71]
	v_mfma_f32_16x16x32_bf16 v[64:67], v[210:213], v[242:245], v[64:67]
	s_setprio 0
	s_barrier
; #define PG8_STAGE(bufoff, gbase, voff) do { _Pragma("unroll") for (int _i = 0; _i < 2; ++_i) \
;         __builtin_amdgcn_global_load_lds((const unsigned*)((const char*)(gbase) + (voff)[_i]), (PG8_LAS unsigned*)(lds + (bufoff) + ldsw + _i * 8192), 16, 0, 0); } while (0)
; #define PG8_LDA(dst, b, h) do { _Pragma("unroll") for (int m = 0; m < 4; ++m) _Pragma("unroll") for (int k = 0; k < 2; ++k) dst[m][k] = *(const PG8_LAS bf16x8*)(lds + PG8_SA(b, h) + aoff + m * 2048 + k * 1024); } while (0)
; #define PG8_MMA(ai, bj, At, Bt) do { __builtin_amdgcn_s_setprio(1); _Pragma("unroll") for (int m = 0; m < 4; ++m) _Pragma("unroll") for (int n = 0; n < 2; ++n) _Pragma("unroll") for (int k = 0; k < 2; ++k) \
;         acc[ai][bj][m][n] = __builtin_amdgcn_mfma_f32_16x16x32_bf16(Bt[n][k], At[m][k], acc[ai][bj][m][n], 0, 0, 0); __builtin_amdgcn_s_setprio(0); } while (0)
; #define PG8_WAIT_V(n) asm volatile("s_waitcnt vmcnt(" #n ")" ::: "memory")
; #define PG8_WAIT_L(n) asm volatile("s_waitcnt lgkmcnt(" #n ")" ::: "memory")
; #define PG8_BAR __builtin_amdgcn_s_barrier()
; #define PG8_SCHED __builtin_amdgcn_sched_barrier(0)
; template <class Epi, class Sched, bool ALIGN_EPI = false, bool SP2 = false>
; __device__ __forceinline__ void gemm_phase(PG8_LAS unsigned char* lds, const Gemm g, const Sched& S, const Epi& E) {
;     ...
;         for (int t = 0; t < nt; t += 2) {
;             const bool last = (t == nt - 2);
;             const char* a1 = cA + (size_t)(t + 1) * kstep;
;             const char* a2 = last ? nA : cA + (size_t)(t + 2) * kstep; const char* b2 = last ? nB : cB + (size_t)(t + 2) * kstep;
;             const char* a3 = a2 + kstep; const char* b3 = b2 + kstep;
;     ...
;             PG8_LDA(At, 1, 1); PG8_STAGE(PG8_SB(1, 0), b3, voffB); PG8_STAGE(PG8_SB(1, 1), b3 + hstep, voffB); PG8_STAGE(PG8_SA(1, 0), a3, voffA);
;             PG8_WAIT_V(8); PG8_WAIT_L(0); PG8_BAR; PG8_MMA(1, 0, At, B0); PG8_MMA(1, 1, At, B1); PG8_BAR; PG8_SCHED;
	s_mov_b32 m0, s43
	v_lshl_add_u64 v[190:191], v[190:191], 0, s[94:95]
	s_add_u32 s2, s2, 0x40080
	ds_read_b128 v[214:217], v163 offset:49152
	ds_read_b128 v[218:221], v163 offset:50176
	ds_read_b128 v[222:225], v163 offset:51200
	ds_read_b128 v[226:229], v163 offset:52224
	ds_read_b128 v[230:233], v163 offset:53248
	ds_read_b128 v[234:237], v163 offset:54272
	ds_read_b128 v[238:241], v163 offset:55296
	ds_read_b128 v[242:245], v163 offset:56320
	global_load_lds_dwordx4 v[190:191], off
	v_lshl_add_u64 v[190:191], v[208:209], 0, s[94:95]
	s_mov_b32 m0, s44
	s_addc_u32 s3, s3, 0
	global_load_lds_dwordx4 v[190:191], off
	v_lshl_add_u64 v[190:191], s[2:3], 0, v[132:133]
	s_mov_b32 m0, s48
	s_nop 0
	global_load_lds_dwordx4 v[190:191], off
	v_lshl_add_u64 v[190:191], s[2:3], 0, v[128:129]
	s_mov_b32 m0, s49
	s_nop 0
	global_load_lds_dwordx4 v[190:191], off
	v_lshl_add_u64 v[190:191], v[246:247], 0, s[94:95]
	s_mov_b32 m0, s45
	s_nop 0
	global_load_lds_dwordx4 v[190:191], off
	v_lshl_add_u64 v[190:191], v[248:249], 0, s[94:95]
	s_mov_b32 m0, s47
	s_nop 0
	global_load_lds_dwordx4 v[190:191], off
	s_waitcnt vmcnt(8)
	s_waitcnt lgkmcnt(0)
	s_barrier
	s_setprio 1
	s_waitcnt lgkmcnt(0)
	v_mfma_f32_16x16x32_bf16 v[60:63], v[140:143], v[214:217], v[60:63]
	v_mfma_f32_16x16x32_bf16 v[56:59], v[170:173], v[214:217], v[56:59]
	v_mfma_f32_16x16x32_bf16 v[44:47], v[140:143], v[222:225], v[44:47]
	v_mfma_f32_16x16x32_bf16 v[40:43], v[170:173], v[222:225], v[40:43]
	v_mfma_f32_16x16x32_bf16 v[28:31], v[140:143], v[230:233], v[28:31]
	v_mfma_f32_16x16x32_bf16 v[24:27], v[170:173], v[230:233], v[24:27]
	v_mfma_f32_16x16x32_bf16 v[12:15], v[140:143], v[238:241], v[12:15]
	v_mfma_f32_16x16x32_bf16 v[8:11], v[170:173], v[238:241], v[8:11]
	v_mfma_f32_16x16x32_bf16 v[60:63], v[166:169], v[218:221], v[60:63]
	v_mfma_f32_16x16x32_bf16 v[56:59], v[174:177], v[218:221], v[56:59]
	v_mfma_f32_16x16x32_bf16 v[44:47], v[166:169], v[226:229], v[44:47]
	v_mfma_f32_16x16x32_bf16 v[40:43], v[174:177], v[226:229], v[40:43]
	v_mfma_f32_16x16x32_bf16 v[28:31], v[166:169], v[234:237], v[28:31]
	v_mfma_f32_16x16x32_bf16 v[24:27], v[174:177], v[234:237], v[24:27]
	v_mfma_f32_16x16x32_bf16 v[12:15], v[166:169], v[242:245], v[12:15]
	v_mfma_f32_16x16x32_bf16 v[8:11], v[174:177], v[242:245], v[8:11]
	s_setprio 0
	s_setprio 1
	v_mfma_f32_16x16x32_bf16 v[52:55], v[178:181], v[214:217], v[52:55]
	v_mfma_f32_16x16x32_bf16 v[48:51], v[186:189], v[214:217], v[48:51]
	v_mfma_f32_16x16x32_bf16 v[36:39], v[178:181], v[222:225], v[36:39]
	v_mfma_f32_16x16x32_bf16 v[32:35], v[186:189], v[222:225], v[32:35]
	v_mfma_f32_16x16x32_bf16 v[20:23], v[178:181], v[230:233], v[20:23]
	v_mfma_f32_16x16x32_bf16 v[16:19], v[186:189], v[230:233], v[16:19]
	v_mfma_f32_16x16x32_bf16 v[4:7], v[178:181], v[238:241], v[4:7]
	v_mfma_f32_16x16x32_bf16 v[0:3], v[186:189], v[238:241], v[0:3]
	v_mfma_f32_16x16x32_bf16 v[52:55], v[182:185], v[218:221], v[52:55]
	v_mfma_f32_16x16x32_bf16 v[48:51], v[210:213], v[218:221], v[48:51]
	v_mfma_f32_16x16x32_bf16 v[36:39], v[182:185], v[226:229], v[36:39]
	v_mfma_f32_16x16x32_bf16 v[32:35], v[210:213], v[226:229], v[32:35]
	v_mfma_f32_16x16x32_bf16 v[20:23], v[182:185], v[234:237], v[20:23]
	v_mfma_f32_16x16x32_bf16 v[16:19], v[210:213], v[234:237], v[16:19]
	v_mfma_f32_16x16x32_bf16 v[4:7], v[182:185], v[242:245], v[4:7]
	v_mfma_f32_16x16x32_bf16 v[0:3], v[210:213], v[242:245], v[0:3]
	s_setprio 0
	s_barrier
	s_add_i32 s55, s55, 2
	s_add_u32 s0, s0, 0x100
	s_addc_u32 s1, s1, 0
	s_add_u32 s53, s53, 0x100
	s_addc_u32 s54, s54, 0
	s_cmp_gt_u32 s55, 13
